# POST phase sample-row units: throw-away loads warm the caches for the later iterations
# speedup vs baseline: 1.1954x; 1.0036x over previous
; __device__ __forceinline__ float bf2f(u16 h) { return __uint_as_float(((unsigned)h) << 16); }
; template <int EPI> ...
;     ...
;       const int hh = nt * 2 + wn;
;       const u16* P = (const u16*)(p.ws + O_P);
;       u16* Y = (u16*)(p.ws + O_Y);
;       const float* bs = (const float*)(p.ws + O_BS);
;       const int ch0 = hh * 64 + (lane & 31), ch1 = ch0 + 32;
;       const float gg0 = p.in[20][ch0], gg1 = p.in[20][ch1];
;       const float gb0 = p.in[21][ch0], gb1 = p.in[21][ch1];
;       const float mu0 = p.in[11][1536 + ch0], mu1 = p.in[11][1536 + ch1];
; #pragma unroll 16
;       for (int i = 0; i < 16; i++) {
;         const int rl = rbase + (i & 3) + 8 * (i >> 2);
;         const int row = m0 + rl;
;         float o0 = bf2f(Y[(size_t)row * 1024 + 256 + ch0]);
;         float o1 = bf2f(Y[(size_t)row * 1024 + 256 + ch1]);
;         float mean = hsum32(o0 + o1) * (1.0f / 64.0f);
;         float d0 = o0 - mean, d1 = o1 - mean;
;         float var = hsum32(d0 * d0 + d1 * d1) * (1.0f / 64.0f);
;         float rstd = rsqrtf(var + 64e-5f);
;         float pv0 = bf2f(P[(size_t)row * 2816 + 256 + 1536 + ch0]);
;         float pv1 = bf2f(P[(size_t)row * 2816 + 256 + 1536 + ch1]);
;         float pp0 = prevP(p, P, row, 1536 + ch0), pp1 = prevP(p, P, row, 1536 + ch1);
;         float vv0 = pv0 + (pp0 - pv0) * mu0, vv1 = pv1 + (pp1 - pv1) * mu1;
;         float b = bs[((size_t)row * 12 + hh) * 4 + 2];
.Lpo_sample:
	s_sub_u32 s11, s6, 64
	s_lshl_b32 s11, s11, 6
	s_lshl_b32 s12, s4, 4
	s_add_u32 s11, s11, s12
	v_lshrrev_b32_e32 v247, 2, v248
	v_add_u32_e32 v247, s11, v247
	v_mul_u32_u24_e32 v247, 0x2800, v247
	v_add_u32_e32 v247, v247, v233
	v_add_u32_e32 v247, 0x1800, v247
	v_add_u32_e32 v236, 0x8000, v230
	v_add_u32_e32 v237, 0x16000, v231
	v_add_u32_e32 v240, 0xa000, v247
	global_load_dwordx4 v[218:221], v236, s[22:23] offset:0
	global_load_dwordx4 v[222:225], v237, s[96:97] offset:0
	global_load_dwordx4 v[218:221], v240, s[20:21] offset:0
	global_load_dwordx4 v[222:225], v240, s[20:21] offset:16
	global_load_dwordx4 v[218:221], v236, s[22:23] offset:64
	global_load_dwordx4 v[222:225], v237, s[96:97] offset:64
	global_load_dwordx4 v[218:221], v240, s[20:21] offset:128
	global_load_dwordx4 v[222:225], v240, s[20:21] offset:144
	v_add_u32_e32 v236, 0x10000, v230
	v_add_u32_e32 v237, 0x2c000, v231
	v_add_u32_e32 v240, 0x14000, v247
	global_load_dwordx4 v[218:221], v236, s[22:23] offset:0
	global_load_dwordx4 v[222:225], v237, s[96:97] offset:0
	global_load_dwordx4 v[218:221], v240, s[20:21] offset:0
	global_load_dwordx4 v[222:225], v240, s[20:21] offset:16
	global_load_dwordx4 v[218:221], v236, s[22:23] offset:64
	global_load_dwordx4 v[222:225], v237, s[96:97] offset:64
	global_load_dwordx4 v[218:221], v240, s[20:21] offset:128
	global_load_dwordx4 v[222:225], v240, s[20:21] offset:144
	v_add_u32_e32 v236, 0x18000, v230
	v_add_u32_e32 v237, 0x42000, v231
	v_add_u32_e32 v240, 0x1e000, v247
	global_load_dwordx4 v[218:221], v236, s[22:23] offset:0
	global_load_dwordx4 v[222:225], v237, s[96:97] offset:0
	global_load_dwordx4 v[218:221], v240, s[20:21] offset:0
	global_load_dwordx4 v[222:225], v240, s[20:21] offset:16
	global_load_dwordx4 v[218:221], v236, s[22:23] offset:64
	global_load_dwordx4 v[222:225], v237, s[96:97] offset:64
	global_load_dwordx4 v[218:221], v240, s[20:21] offset:128
	global_load_dwordx4 v[222:225], v240, s[20:21] offset:144
	v_add_u32_e32 v236, 0x0, v230
	v_add_u32_e32 v237, 0x0, v231
	v_add_u32_e32 v240, 0x0, v247
	global_load_dwordx4 v[218:221], v236, s[22:23] offset:128
	global_load_dwordx4 v[222:225], v237, s[96:97] offset:128
	global_load_dwordx4 v[218:221], v240, s[20:21] offset:256
	global_load_dwordx4 v[222:225], v240, s[20:21] offset:272
	global_load_dwordx4 v[218:221], v236, s[22:23] offset:192
	global_load_dwordx4 v[222:225], v237, s[96:97] offset:192
	global_load_dwordx4 v[218:221], v240, s[20:21] offset:384
	global_load_dwordx4 v[222:225], v240, s[20:21] offset:400
	v_add_u32_e32 v236, 0x8000, v230
	v_add_u32_e32 v237, 0x16000, v231
	v_add_u32_e32 v240, 0xa000, v247
	global_load_dwordx4 v[218:221], v236, s[22:23] offset:128
	global_load_dwordx4 v[222:225], v237, s[96:97] offset:128
	global_load_dwordx4 v[218:221], v240, s[20:21] offset:256
	global_load_dwordx4 v[222:225], v240, s[20:21] offset:272
	global_load_dwordx4 v[218:221], v236, s[22:23] offset:192
	global_load_dwordx4 v[222:225], v237, s[96:97] offset:192
	global_load_dwordx4 v[218:221], v240, s[20:21] offset:384
	global_load_dwordx4 v[222:225], v240, s[20:21] offset:400
	v_add_u32_e32 v236, 0x10000, v230
	v_add_u32_e32 v237, 0x2c000, v231
	v_add_u32_e32 v240, 0x14000, v247
	global_load_dwordx4 v[218:221], v236, s[22:23] offset:128
	global_load_dwordx4 v[222:225], v237, s[96:97] offset:128
	global_load_dwordx4 v[218:221], v240, s[20:21] offset:256
	global_load_dwordx4 v[222:225], v240, s[20:21] offset:272
	global_load_dwordx4 v[218:221], v236, s[22:23] offset:192
	global_load_dwordx4 v[222:225], v237, s[96:97] offset:192
	global_load_dwordx4 v[218:221], v240, s[20:21] offset:384
	global_load_dwordx4 v[222:225], v240, s[20:21] offset:400
	v_add_u32_e32 v236, 0x18000, v230
	v_add_u32_e32 v237, 0x42000, v231
	v_add_u32_e32 v240, 0x1e000, v247
	global_load_dwordx4 v[218:221], v236, s[22:23] offset:128
	global_load_dwordx4 v[222:225], v237, s[96:97] offset:128
	global_load_dwordx4 v[218:221], v240, s[20:21] offset:256
	global_load_dwordx4 v[222:225], v240, s[20:21] offset:272
	global_load_dwordx4 v[218:221], v236, s[22:23] offset:192
	global_load_dwordx4 v[222:225], v237, s[96:97] offset:192
	global_load_dwordx4 v[218:221], v240, s[20:21] offset:384
	global_load_dwordx4 v[222:225], v240, s[20:21] offset:400
	global_load_dwordx4 v[130:133], v233, s[2:3] offset:0
	global_load_dwordx4 v[134:137], v233, s[2:3] offset:16
	global_load_dwordx4 v[138:141], v233, s[2:3] offset:128
	global_load_dwordx4 v[142:145], v233, s[2:3] offset:144
	global_load_dwordx4 v[146:149], v233, s[16:17] offset:0
	global_load_dwordx4 v[150:153], v233, s[16:17] offset:16
	global_load_dwordx4 v[154:157], v233, s[16:17] offset:128
	global_load_dwordx4 v[158:161], v233, s[16:17] offset:144
	global_load_dwordx4 v[162:165], v233, s[0:1] offset:0
	global_load_dwordx4 v[166:169], v233, s[0:1] offset:16
	global_load_dwordx4 v[170:173], v233, s[0:1] offset:128
	global_load_dwordx4 v[174:177], v233, s[0:1] offset:144
	v_add_u32_e32 v236, 0x0, v230
	v_add_u32_e32 v237, 0x0, v231
	v_subrev_u32_e32 v240, 0x1600, v237
	global_load_dwordx4 v[178:181], v236, s[22:23] offset:0
	global_load_dwordx4 v[182:185], v236, s[22:23] offset:64
	global_load_dwordx4 v[186:189], v237, s[96:97] offset:0
	global_load_dwordx4 v[190:193], v237, s[96:97] offset:64
	global_load_dwordx4 v[194:197], v240, s[96:97] offset:0
	global_load_dwordx4 v[198:201], v240, s[96:97] offset:64
	v_add_u32_e32 v236, 0x0, v232
	s_nop 0
	global_load_dword v234, v236, s[96:97] offset:0
	v_add_u32_e32 v237, 0x0, v247
	global_load_dwordx4 v[202:205], v237, s[20:21] offset:0
	global_load_dwordx4 v[206:209], v237, s[20:21] offset:16
	global_load_dwordx4 v[210:213], v237, s[20:21] offset:128
	global_load_dwordx4 v[214:217], v237, s[20:21] offset:144
	s_waitcnt vmcnt(0)
; __device__ __forceinline__ float bf2f(u16 h) { return __uint_as_float(((unsigned)h) << 16); }
; template <int EPI> ...
;     ...
;         float o0 = bf2f(Y[(size_t)row * 1024 + 256 + ch0]);
;         float o1 = bf2f(Y[(size_t)row * 1024 + 256 + ch1]);
;         float mean = hsum32(o0 + o1) * (1.0f / 64.0f);
;         float d0 = o0 - mean, d1 = o1 - mean;
;         float var = hsum32(d0 * d0 + d1 * d1) * (1.0f / 64.0f);
;         float rstd = rsqrtf(var + 64e-5f);
;         float pv0 = bf2f(P[(size_t)row * 2816 + 256 + 1536 + ch0]);
;         float pv1 = bf2f(P[(size_t)row * 2816 + 256 + 1536 + ch1]);
;         float pp0 = prevP(p, P, row, 1536 + ch0), pp1 = prevP(p, P, row, 1536 + ch1);
;         float vv0 = pv0 + (pp0 - pv0) * mu0, vv1 = pv1 + (pp1 - pv1) * mu1;
;         float b = bs[((size_t)row * 12 + hh) * 4 + 2];
;         float y0 = (d0 * rstd * gg0 + gb0 + b * vv0) * acc0[i];
;         float y1 = (d1 * rstd * gg1 + gb1 + b * vv1) * acc1[i];
	v_lshlrev_b32_e32 v240, 16, v178
	v_and_b32_e32 v241, 0xffff0000, v178
	v_add_f32_e32 v244, v240, v241
	v_lshlrev_b32_e32 v240, 16, v179
	v_and_b32_e32 v241, 0xffff0000, v179
	v_add_f32_e32 v244, v244, v240
	v_add_f32_e32 v244, v244, v241
	v_lshlrev_b32_e32 v240, 16, v180
	v_and_b32_e32 v241, 0xffff0000, v180
	v_add_f32_e32 v244, v244, v240
	v_add_f32_e32 v244, v244, v241
	v_lshlrev_b32_e32 v240, 16, v181
	v_and_b32_e32 v241, 0xffff0000, v181
	v_add_f32_e32 v244, v244, v240
	v_add_f32_e32 v244, v244, v241
	v_lshlrev_b32_e32 v240, 16, v182
	v_and_b32_e32 v241, 0xffff0000, v182
	v_add_f32_e32 v244, v244, v240
	v_add_f32_e32 v244, v244, v241
	v_lshlrev_b32_e32 v240, 16, v183
	v_and_b32_e32 v241, 0xffff0000, v183
	v_add_f32_e32 v244, v244, v240
	v_add_f32_e32 v244, v244, v241
	v_lshlrev_b32_e32 v240, 16, v184
	v_and_b32_e32 v241, 0xffff0000, v184
	v_add_f32_e32 v244, v244, v240
	v_add_f32_e32 v244, v244, v241
	v_lshlrev_b32_e32 v240, 16, v185
	v_and_b32_e32 v241, 0xffff0000, v185
	v_add_f32_e32 v244, v244, v240
	v_add_f32_e32 v244, v244, v241
	v_mov_b32_e32 v240, v244
	s_nop 1
	v_permlane16_swap_b32_e32 v240, v244
	v_add_f32_e32 v244, v244, v240
	v_mov_b32_e32 v240, v244
	s_nop 1
	v_permlane32_swap_b32_e32 v240, v244
	v_add_f32_e32 v244, v244, v240
	v_mul_f32_e32 v238, 0x3c800000, v244
	v_lshlrev_b32_e32 v240, 16, v178
	v_and_b32_e32 v241, 0xffff0000, v178
	v_sub_f32_e32 v240, v240, v238
	v_sub_f32_e32 v241, v241, v238
	v_mul_f32_e32 v245, v240, v240
	v_fmac_f32_e32 v245, v241, v241
	v_lshlrev_b32_e32 v240, 16, v179
	v_and_b32_e32 v241, 0xffff0000, v179
	v_sub_f32_e32 v240, v240, v238
	v_sub_f32_e32 v241, v241, v238
	v_fmac_f32_e32 v245, v240, v240
	v_fmac_f32_e32 v245, v241, v241
	v_lshlrev_b32_e32 v240, 16, v180
	v_and_b32_e32 v241, 0xffff0000, v180
	v_sub_f32_e32 v240, v240, v238
	v_sub_f32_e32 v241, v241, v238
	v_fmac_f32_e32 v245, v240, v240
	v_fmac_f32_e32 v245, v241, v241
	v_lshlrev_b32_e32 v240, 16, v181
	v_and_b32_e32 v241, 0xffff0000, v181
	v_sub_f32_e32 v240, v240, v238
	v_sub_f32_e32 v241, v241, v238
	v_fmac_f32_e32 v245, v240, v240
	v_fmac_f32_e32 v245, v241, v241
	v_lshlrev_b32_e32 v240, 16, v182
	v_and_b32_e32 v241, 0xffff0000, v182
	v_sub_f32_e32 v240, v240, v238
	v_sub_f32_e32 v241, v241, v238
	v_fmac_f32_e32 v245, v240, v240
	v_fmac_f32_e32 v245, v241, v241
	v_lshlrev_b32_e32 v240, 16, v183
	v_and_b32_e32 v241, 0xffff0000, v183
	v_sub_f32_e32 v240, v240, v238
	v_sub_f32_e32 v241, v241, v238
	v_fmac_f32_e32 v245, v240, v240
	v_fmac_f32_e32 v245, v241, v241
	v_lshlrev_b32_e32 v240, 16, v184
	v_and_b32_e32 v241, 0xffff0000, v184
	v_sub_f32_e32 v240, v240, v238
	v_sub_f32_e32 v241, v241, v238
	v_fmac_f32_e32 v245, v240, v240
	v_fmac_f32_e32 v245, v241, v241
	v_lshlrev_b32_e32 v240, 16, v185
	v_and_b32_e32 v241, 0xffff0000, v185
	v_sub_f32_e32 v240, v240, v238
	v_sub_f32_e32 v241, v241, v238
	v_fmac_f32_e32 v245, v240, v240
	v_fmac_f32_e32 v245, v241, v241
	v_mov_b32_e32 v240, v245
	s_nop 1
	v_permlane16_swap_b32_e32 v240, v245
	v_add_f32_e32 v245, v245, v240
	v_mov_b32_e32 v240, v245
	s_nop 1
	v_permlane32_swap_b32_e32 v240, v245
	v_add_f32_e32 v245, v245, v240
	v_mov_b32_e32 v240, 0x3a27c5ac
	v_fmamk_f32 v245, v245, 0x3c800000, v240
	v_rsq_f32_e32 v239, v245
	v_and_b32_e32 v240, 3, v248
	v_cmp_eq_u32_e32 vcc, 0, v240
	s_nop 1
	v_lshlrev_b32_e32 v240, 16, v178
	v_and_b32_e32 v244, 0xffff0000, v178
	v_sub_f32_e32 v240, v240, v238
	v_sub_f32_e32 v244, v244, v238
	v_mul_f32_e32 v240, v240, v239
	v_mul_f32_e32 v244, v244, v239
	v_fma_f32 v240, v130, v240, v146
	v_fma_f32 v244, v131, v244, v147
	v_lshlrev_b32_e32 v241, 16, v186
	v_and_b32_e32 v245, 0xffff0000, v186
	v_lshlrev_b32_e32 v243, 16, v194
	v_and_b32_e32 v246, 0xffff0000, v194
	v_cndmask_b32_e32 v243, v243, v202, vcc
	v_cndmask_b32_e32 v246, v246, v203, vcc
	v_sub_f32_e32 v243, v243, v241
	v_sub_f32_e32 v246, v246, v245
	v_fmac_f32_e32 v241, v162, v243
	v_fmac_f32_e32 v245, v163, v246
	v_fmac_f32_e32 v240, v234, v241
	v_fmac_f32_e32 v244, v234, v245
	v_mul_f32_e32 v0, v0, v240
	v_mul_f32_e32 v1, v1, v244
	v_lshlrev_b32_e32 v240, 16, v179
	v_and_b32_e32 v244, 0xffff0000, v179
	v_sub_f32_e32 v240, v240, v238
	v_sub_f32_e32 v244, v244, v238
	v_mul_f32_e32 v240, v240, v239
	v_mul_f32_e32 v244, v244, v239
	v_fma_f32 v240, v132, v240, v148
	v_fma_f32 v244, v133, v244, v149
	v_lshlrev_b32_e32 v241, 16, v187
	v_and_b32_e32 v245, 0xffff0000, v187
	v_lshlrev_b32_e32 v243, 16, v195
	v_and_b32_e32 v246, 0xffff0000, v195
	v_cndmask_b32_e32 v243, v243, v204, vcc
	v_cndmask_b32_e32 v246, v246, v205, vcc
	v_sub_f32_e32 v243, v243, v241
	v_sub_f32_e32 v246, v246, v245
	v_fmac_f32_e32 v241, v164, v243
	v_fmac_f32_e32 v245, v165, v246
	v_fmac_f32_e32 v240, v234, v241
	v_fmac_f32_e32 v244, v234, v245
	v_mul_f32_e32 v2, v2, v240
	v_mul_f32_e32 v3, v3, v244
	v_lshlrev_b32_e32 v240, 16, v180
	v_and_b32_e32 v244, 0xffff0000, v180
	v_sub_f32_e32 v240, v240, v238
	v_sub_f32_e32 v244, v244, v238
	v_mul_f32_e32 v240, v240, v239
	v_mul_f32_e32 v244, v244, v239
	v_fma_f32 v240, v134, v240, v150
	v_fma_f32 v244, v135, v244, v151
	v_lshlrev_b32_e32 v241, 16, v188
	v_and_b32_e32 v245, 0xffff0000, v188
	v_lshlrev_b32_e32 v243, 16, v196
	v_and_b32_e32 v246, 0xffff0000, v196
	v_cndmask_b32_e32 v243, v243, v206, vcc
	v_cndmask_b32_e32 v246, v246, v207, vcc
	v_sub_f32_e32 v243, v243, v241
	v_sub_f32_e32 v246, v246, v245
	v_fmac_f32_e32 v241, v166, v243
	v_fmac_f32_e32 v245, v167, v246
	v_fmac_f32_e32 v240, v234, v241
	v_fmac_f32_e32 v244, v234, v245
	v_mul_f32_e32 v4, v4, v240
	v_mul_f32_e32 v5, v5, v244
	v_lshlrev_b32_e32 v240, 16, v181
	v_and_b32_e32 v244, 0xffff0000, v181
	v_sub_f32_e32 v240, v240, v238
; __device__ __forceinline__ float bf2f(u16 h) { return __uint_as_float(((unsigned)h) << 16); }
; template <int EPI> ...
;     ...
;         float pv0 = bf2f(P[(size_t)row * 2816 + 256 + 1536 + ch0]);
;         float pv1 = bf2f(P[(size_t)row * 2816 + 256 + 1536 + ch1]);
;         float pp0 = prevP(p, P, row, 1536 + ch0), pp1 = prevP(p, P, row, 1536 + ch1);
;         float vv0 = pv0 + (pp0 - pv0) * mu0, vv1 = pv1 + (pp1 - pv1) * mu1;
;         float b = bs[((size_t)row * 12 + hh) * 4 + 2];
;         float y0 = (d0 * rstd * gg0 + gb0 + b * vv0) * acc0[i];
;         float y1 = (d1 * rstd * gg1 + gb1 + b * vv1) * acc1[i];
;         Y[(size_t)row * 1024 + 256 + ch0] = f2bf(y0);
;         Y[(size_t)row * 1024 + 256 + ch1] = f2bf(y1);
;       }
	v_sub_f32_e32 v244, v244, v238
	v_mul_f32_e32 v240, v240, v239
	v_mul_f32_e32 v244, v244, v239
	v_fma_f32 v240, v136, v240, v152
	v_fma_f32 v244, v137, v244, v153
	v_lshlrev_b32_e32 v241, 16, v189
	v_and_b32_e32 v245, 0xffff0000, v189
	v_lshlrev_b32_e32 v243, 16, v197
	v_and_b32_e32 v246, 0xffff0000, v197
	v_cndmask_b32_e32 v243, v243, v208, vcc
	v_cndmask_b32_e32 v246, v246, v209, vcc
	v_sub_f32_e32 v243, v243, v241
	v_sub_f32_e32 v246, v246, v245
	v_fmac_f32_e32 v241, v168, v243
	v_fmac_f32_e32 v245, v169, v246
	v_fmac_f32_e32 v240, v234, v241
	v_fmac_f32_e32 v244, v234, v245
	v_mul_f32_e32 v6, v6, v240
	v_mul_f32_e32 v7, v7, v244
	v_cvt_pk_bf16_f32 v0, v0, v1
	v_cvt_pk_bf16_f32 v1, v2, v3
	v_cvt_pk_bf16_f32 v2, v4, v5
	v_cvt_pk_bf16_f32 v3, v6, v7
	v_add_u32_e32 v236, 0x0, v230
	s_nop 0
	global_store_dwordx4 v236, v[0:3], s[22:23] offset:0
	v_lshlrev_b32_e32 v240, 16, v182
	v_and_b32_e32 v244, 0xffff0000, v182
	v_sub_f32_e32 v240, v240, v238
	v_sub_f32_e32 v244, v244, v238
	v_mul_f32_e32 v240, v240, v239
	v_mul_f32_e32 v244, v244, v239
	v_fma_f32 v240, v138, v240, v154
	v_fma_f32 v244, v139, v244, v155
	v_lshlrev_b32_e32 v241, 16, v190
	v_and_b32_e32 v245, 0xffff0000, v190
	v_lshlrev_b32_e32 v243, 16, v198
	v_and_b32_e32 v246, 0xffff0000, v198
	v_cndmask_b32_e32 v243, v243, v210, vcc
	v_cndmask_b32_e32 v246, v246, v211, vcc
	v_sub_f32_e32 v243, v243, v241
	v_sub_f32_e32 v246, v246, v245
	v_fmac_f32_e32 v241, v170, v243
	v_fmac_f32_e32 v245, v171, v246
	v_fmac_f32_e32 v240, v234, v241
	v_fmac_f32_e32 v244, v234, v245
	v_mul_f32_e32 v8, v8, v240
	v_mul_f32_e32 v9, v9, v244
	v_lshlrev_b32_e32 v240, 16, v183
	v_and_b32_e32 v244, 0xffff0000, v183
	v_sub_f32_e32 v240, v240, v238
	v_sub_f32_e32 v244, v244, v238
	v_mul_f32_e32 v240, v240, v239
	v_mul_f32_e32 v244, v244, v239
	v_fma_f32 v240, v140, v240, v156
	v_fma_f32 v244, v141, v244, v157
	v_lshlrev_b32_e32 v241, 16, v191
	v_and_b32_e32 v245, 0xffff0000, v191
	v_lshlrev_b32_e32 v243, 16, v199
	v_and_b32_e32 v246, 0xffff0000, v199
	v_cndmask_b32_e32 v243, v243, v212, vcc
	v_cndmask_b32_e32 v246, v246, v213, vcc
	v_sub_f32_e32 v243, v243, v241
	v_sub_f32_e32 v246, v246, v245
	v_fmac_f32_e32 v241, v172, v243
	v_fmac_f32_e32 v245, v173, v246
	v_fmac_f32_e32 v240, v234, v241
	v_fmac_f32_e32 v244, v234, v245
	v_mul_f32_e32 v10, v10, v240
	v_mul_f32_e32 v11, v11, v244
	v_lshlrev_b32_e32 v240, 16, v184
	v_and_b32_e32 v244, 0xffff0000, v184
	v_sub_f32_e32 v240, v240, v238
	v_sub_f32_e32 v244, v244, v238
	v_mul_f32_e32 v240, v240, v239
	v_mul_f32_e32 v244, v244, v239
	v_fma_f32 v240, v142, v240, v158
	v_fma_f32 v244, v143, v244, v159
	v_lshlrev_b32_e32 v241, 16, v192
	v_and_b32_e32 v245, 0xffff0000, v192
	v_lshlrev_b32_e32 v243, 16, v200
	v_and_b32_e32 v246, 0xffff0000, v200
	v_cndmask_b32_e32 v243, v243, v214, vcc
	v_cndmask_b32_e32 v246, v246, v215, vcc
	v_sub_f32_e32 v243, v243, v241
	v_sub_f32_e32 v246, v246, v245
	v_fmac_f32_e32 v241, v174, v243
	v_fmac_f32_e32 v245, v175, v246
	v_fmac_f32_e32 v240, v234, v241
	v_fmac_f32_e32 v244, v234, v245
	v_mul_f32_e32 v12, v12, v240
	v_mul_f32_e32 v13, v13, v244
	v_lshlrev_b32_e32 v240, 16, v185
	v_and_b32_e32 v244, 0xffff0000, v185
	v_sub_f32_e32 v240, v240, v238
	v_sub_f32_e32 v244, v244, v238
	v_mul_f32_e32 v240, v240, v239
	v_mul_f32_e32 v244, v244, v239
	v_fma_f32 v240, v144, v240, v160
	v_fma_f32 v244, v145, v244, v161
	v_lshlrev_b32_e32 v241, 16, v193
	v_and_b32_e32 v245, 0xffff0000, v193
	v_lshlrev_b32_e32 v243, 16, v201
	v_and_b32_e32 v246, 0xffff0000, v201
	v_cndmask_b32_e32 v243, v243, v216, vcc
	v_cndmask_b32_e32 v246, v246, v217, vcc
	v_sub_f32_e32 v243, v243, v241
	v_sub_f32_e32 v246, v246, v245
	v_fmac_f32_e32 v241, v176, v243
	v_fmac_f32_e32 v245, v177, v246
	v_fmac_f32_e32 v240, v234, v241
	v_fmac_f32_e32 v244, v234, v245
	v_mul_f32_e32 v14, v14, v240
	v_mul_f32_e32 v15, v15, v244
	v_cvt_pk_bf16_f32 v8, v8, v9
	v_cvt_pk_bf16_f32 v9, v10, v11
	v_cvt_pk_bf16_f32 v10, v12, v13
	v_cvt_pk_bf16_f32 v11, v14, v15
	v_add_u32_e32 v236, 0x0, v230
	s_nop 0
	global_store_dwordx4 v236, v[8:11], s[22:23] offset:64
	v_add_u32_e32 v236, 0x8000, v230
	v_add_u32_e32 v237, 0x16000, v231
	v_subrev_u32_e32 v240, 0x1600, v237
	global_load_dwordx4 v[178:181], v236, s[22:23] offset:0
	global_load_dwordx4 v[182:185], v236, s[22:23] offset:64
	global_load_dwordx4 v[186:189], v237, s[96:97] offset:0
	global_load_dwordx4 v[190:193], v237, s[96:97] offset:64
	global_load_dwordx4 v[194:197], v240, s[96:97] offset:0
	global_load_dwordx4 v[198:201], v240, s[96:97] offset:64
	v_add_u32_e32 v236, 0xc00, v232
	s_nop 0
	global_load_dword v234, v236, s[96:97] offset:0
	v_add_u32_e32 v237, 0xa000, v247
	global_load_dwordx4 v[202:205], v237, s[20:21] offset:0
	global_load_dwordx4 v[206:209], v237, s[20:21] offset:16
	global_load_dwordx4 v[210:213], v237, s[20:21] offset:128
	global_load_dwordx4 v[214:217], v237, s[20:21] offset:144
	s_waitcnt vmcnt(0)
; __device__ __forceinline__ float bf2f(u16 h) { return __uint_as_float(((unsigned)h) << 16); }
; template <int EPI> ...
;     ...
;         float o0 = bf2f(Y[(size_t)row * 1024 + 256 + ch0]);
;         float o1 = bf2f(Y[(size_t)row * 1024 + 256 + ch1]);
;         float mean = hsum32(o0 + o1) * (1.0f / 64.0f);
;         float d0 = o0 - mean, d1 = o1 - mean;
;         float var = hsum32(d0 * d0 + d1 * d1) * (1.0f / 64.0f);
;         float rstd = rsqrtf(var + 64e-5f);
;         float pv0 = bf2f(P[(size_t)row * 2816 + 256 + 1536 + ch0]);
;         float pv1 = bf2f(P[(size_t)row * 2816 + 256 + 1536 + ch1]);
;         float pp0 = prevP(p, P, row, 1536 + ch0), pp1 = prevP(p, P, row, 1536 + ch1);
;         float vv0 = pv0 + (pp0 - pv0) * mu0, vv1 = pv1 + (pp1 - pv1) * mu1;
;         float b = bs[((size_t)row * 12 + hh) * 4 + 2];
;         float y0 = (d0 * rstd * gg0 + gb0 + b * vv0) * acc0[i];
;         float y1 = (d1 * rstd * gg1 + gb1 + b * vv1) * acc1[i];
	v_lshlrev_b32_e32 v240, 16, v178
	v_and_b32_e32 v241, 0xffff0000, v178
	v_add_f32_e32 v244, v240, v241
	v_lshlrev_b32_e32 v240, 16, v179
	v_and_b32_e32 v241, 0xffff0000, v179
	v_add_f32_e32 v244, v244, v240
	v_add_f32_e32 v244, v244, v241
	v_lshlrev_b32_e32 v240, 16, v180
	v_and_b32_e32 v241, 0xffff0000, v180
	v_add_f32_e32 v244, v244, v240
	v_add_f32_e32 v244, v244, v241
	v_lshlrev_b32_e32 v240, 16, v181
	v_and_b32_e32 v241, 0xffff0000, v181
	v_add_f32_e32 v244, v244, v240
	v_add_f32_e32 v244, v244, v241
	v_lshlrev_b32_e32 v240, 16, v182
	v_and_b32_e32 v241, 0xffff0000, v182
	v_add_f32_e32 v244, v244, v240
	v_add_f32_e32 v244, v244, v241
	v_lshlrev_b32_e32 v240, 16, v183
	v_and_b32_e32 v241, 0xffff0000, v183
	v_add_f32_e32 v244, v244, v240
	v_add_f32_e32 v244, v244, v241
	v_lshlrev_b32_e32 v240, 16, v184
	v_and_b32_e32 v241, 0xffff0000, v184
	v_add_f32_e32 v244, v244, v240
	v_add_f32_e32 v244, v244, v241
	v_lshlrev_b32_e32 v240, 16, v185
	v_and_b32_e32 v241, 0xffff0000, v185
	v_add_f32_e32 v244, v244, v240
	v_add_f32_e32 v244, v244, v241
	v_mov_b32_e32 v240, v244
	s_nop 1
	v_permlane16_swap_b32_e32 v240, v244
	v_add_f32_e32 v244, v244, v240
	v_mov_b32_e32 v240, v244
	s_nop 1
	v_permlane32_swap_b32_e32 v240, v244
	v_add_f32_e32 v244, v244, v240
	v_mul_f32_e32 v238, 0x3c800000, v244
	v_lshlrev_b32_e32 v240, 16, v178
	v_and_b32_e32 v241, 0xffff0000, v178
	v_sub_f32_e32 v240, v240, v238
	v_sub_f32_e32 v241, v241, v238
	v_mul_f32_e32 v245, v240, v240
	v_fmac_f32_e32 v245, v241, v241
	v_lshlrev_b32_e32 v240, 16, v179
	v_and_b32_e32 v241, 0xffff0000, v179
	v_sub_f32_e32 v240, v240, v238
	v_sub_f32_e32 v241, v241, v238
	v_fmac_f32_e32 v245, v240, v240
	v_fmac_f32_e32 v245, v241, v241
	v_lshlrev_b32_e32 v240, 16, v180
	v_and_b32_e32 v241, 0xffff0000, v180
	v_sub_f32_e32 v240, v240, v238
	v_sub_f32_e32 v241, v241, v238
	v_fmac_f32_e32 v245, v240, v240
	v_fmac_f32_e32 v245, v241, v241
	v_lshlrev_b32_e32 v240, 16, v181
	v_and_b32_e32 v241, 0xffff0000, v181
	v_sub_f32_e32 v240, v240, v238
	v_sub_f32_e32 v241, v241, v238
	v_fmac_f32_e32 v245, v240, v240
	v_fmac_f32_e32 v245, v241, v241
	v_lshlrev_b32_e32 v240, 16, v182
	v_and_b32_e32 v241, 0xffff0000, v182
	v_sub_f32_e32 v240, v240, v238
	v_sub_f32_e32 v241, v241, v238
	v_fmac_f32_e32 v245, v240, v240
	v_fmac_f32_e32 v245, v241, v241
	v_lshlrev_b32_e32 v240, 16, v183
	v_and_b32_e32 v241, 0xffff0000, v183
	v_sub_f32_e32 v240, v240, v238
	v_sub_f32_e32 v241, v241, v238
	v_fmac_f32_e32 v245, v240, v240
	v_fmac_f32_e32 v245, v241, v241
	v_lshlrev_b32_e32 v240, 16, v184
	v_and_b32_e32 v241, 0xffff0000, v184
	v_sub_f32_e32 v240, v240, v238
	v_sub_f32_e32 v241, v241, v238
	v_fmac_f32_e32 v245, v240, v240
	v_fmac_f32_e32 v245, v241, v241
	v_lshlrev_b32_e32 v240, 16, v185
	v_and_b32_e32 v241, 0xffff0000, v185
	v_sub_f32_e32 v240, v240, v238
	v_sub_f32_e32 v241, v241, v238
	v_fmac_f32_e32 v245, v240, v240
	v_fmac_f32_e32 v245, v241, v241
	v_mov_b32_e32 v240, v245
	s_nop 1
	v_permlane16_swap_b32_e32 v240, v245
	v_add_f32_e32 v245, v245, v240
	v_mov_b32_e32 v240, v245
	s_nop 1
	v_permlane32_swap_b32_e32 v240, v245
	v_add_f32_e32 v245, v245, v240
	v_mov_b32_e32 v240, 0x3a27c5ac
	v_fmamk_f32 v245, v245, 0x3c800000, v240
	v_rsq_f32_e32 v239, v245
	v_and_b32_e32 v240, 3, v248
	v_cmp_eq_u32_e32 vcc, 0, v240
	s_nop 1
	v_lshlrev_b32_e32 v240, 16, v178
	v_and_b32_e32 v244, 0xffff0000, v178
	v_sub_f32_e32 v240, v240, v238
	v_sub_f32_e32 v244, v244, v238
	v_mul_f32_e32 v240, v240, v239
	v_mul_f32_e32 v244, v244, v239
	v_fma_f32 v240, v130, v240, v146
	v_fma_f32 v244, v131, v244, v147
	v_lshlrev_b32_e32 v241, 16, v186
	v_and_b32_e32 v245, 0xffff0000, v186
	v_lshlrev_b32_e32 v243, 16, v194
	v_and_b32_e32 v246, 0xffff0000, v194
	v_cndmask_b32_e32 v243, v243, v202, vcc
	v_cndmask_b32_e32 v246, v246, v203, vcc
	v_sub_f32_e32 v243, v243, v241
	v_sub_f32_e32 v246, v246, v245
	v_fmac_f32_e32 v241, v162, v243
	v_fmac_f32_e32 v245, v163, v246
	v_fmac_f32_e32 v240, v234, v241
	v_fmac_f32_e32 v244, v234, v245
	v_mul_f32_e32 v32, v32, v240
	v_mul_f32_e32 v33, v33, v244
	v_lshlrev_b32_e32 v240, 16, v179
	v_and_b32_e32 v244, 0xffff0000, v179
	v_sub_f32_e32 v240, v240, v238
	v_sub_f32_e32 v244, v244, v238
	v_mul_f32_e32 v240, v240, v239
	v_mul_f32_e32 v244, v244, v239
	v_fma_f32 v240, v132, v240, v148
	v_fma_f32 v244, v133, v244, v149
	v_lshlrev_b32_e32 v241, 16, v187
	v_and_b32_e32 v245, 0xffff0000, v187
	v_lshlrev_b32_e32 v243, 16, v195
	v_and_b32_e32 v246, 0xffff0000, v195
	v_cndmask_b32_e32 v243, v243, v204, vcc
	v_cndmask_b32_e32 v246, v246, v205, vcc
	v_sub_f32_e32 v243, v243, v241
	v_sub_f32_e32 v246, v246, v245
	v_fmac_f32_e32 v241, v164, v243
	v_fmac_f32_e32 v245, v165, v246
	v_fmac_f32_e32 v240, v234, v241
	v_fmac_f32_e32 v244, v234, v245
	v_mul_f32_e32 v34, v34, v240
	v_mul_f32_e32 v35, v35, v244
	v_lshlrev_b32_e32 v240, 16, v180
	v_and_b32_e32 v244, 0xffff0000, v180
	v_sub_f32_e32 v240, v240, v238
	v_sub_f32_e32 v244, v244, v238
	v_mul_f32_e32 v240, v240, v239
	v_mul_f32_e32 v244, v244, v239
	v_fma_f32 v240, v134, v240, v150
	v_fma_f32 v244, v135, v244, v151
	v_lshlrev_b32_e32 v241, 16, v188
	v_and_b32_e32 v245, 0xffff0000, v188
	v_lshlrev_b32_e32 v243, 16, v196
	v_and_b32_e32 v246, 0xffff0000, v196
	v_cndmask_b32_e32 v243, v243, v206, vcc
	v_cndmask_b32_e32 v246, v246, v207, vcc
	v_sub_f32_e32 v243, v243, v241
	v_sub_f32_e32 v246, v246, v245
	v_fmac_f32_e32 v241, v166, v243
	v_fmac_f32_e32 v245, v167, v246
	v_fmac_f32_e32 v240, v234, v241
	v_fmac_f32_e32 v244, v234, v245
	v_mul_f32_e32 v36, v36, v240
	v_mul_f32_e32 v37, v37, v244
	v_lshlrev_b32_e32 v240, 16, v181
	v_and_b32_e32 v244, 0xffff0000, v181
	v_sub_f32_e32 v240, v240, v238
; __device__ __forceinline__ float bf2f(u16 h) { return __uint_as_float(((unsigned)h) << 16); }
; template <int EPI> ...
;     ...
;         float pv0 = bf2f(P[(size_t)row * 2816 + 256 + 1536 + ch0]);
;         float pv1 = bf2f(P[(size_t)row * 2816 + 256 + 1536 + ch1]);
;         float pp0 = prevP(p, P, row, 1536 + ch0), pp1 = prevP(p, P, row, 1536 + ch1);
;         float vv0 = pv0 + (pp0 - pv0) * mu0, vv1 = pv1 + (pp1 - pv1) * mu1;
;         float b = bs[((size_t)row * 12 + hh) * 4 + 2];
;         float y0 = (d0 * rstd * gg0 + gb0 + b * vv0) * acc0[i];
;         float y1 = (d1 * rstd * gg1 + gb1 + b * vv1) * acc1[i];
;         Y[(size_t)row * 1024 + 256 + ch0] = f2bf(y0);
;         Y[(size_t)row * 1024 + 256 + ch1] = f2bf(y1);
;       }
	v_sub_f32_e32 v244, v244, v238
	v_mul_f32_e32 v240, v240, v239
	v_mul_f32_e32 v244, v244, v239
	v_fma_f32 v240, v136, v240, v152
	v_fma_f32 v244, v137, v244, v153
	v_lshlrev_b32_e32 v241, 16, v189
	v_and_b32_e32 v245, 0xffff0000, v189
	v_lshlrev_b32_e32 v243, 16, v197
	v_and_b32_e32 v246, 0xffff0000, v197
	v_cndmask_b32_e32 v243, v243, v208, vcc
	v_cndmask_b32_e32 v246, v246, v209, vcc
	v_sub_f32_e32 v243, v243, v241
	v_sub_f32_e32 v246, v246, v245
	v_fmac_f32_e32 v241, v168, v243
	v_fmac_f32_e32 v245, v169, v246
	v_fmac_f32_e32 v240, v234, v241
	v_fmac_f32_e32 v244, v234, v245
	v_mul_f32_e32 v38, v38, v240
	v_mul_f32_e32 v39, v39, v244
	v_cvt_pk_bf16_f32 v32, v32, v33
	v_cvt_pk_bf16_f32 v33, v34, v35
	v_cvt_pk_bf16_f32 v34, v36, v37
	v_cvt_pk_bf16_f32 v35, v38, v39
	v_add_u32_e32 v236, 0x8000, v230
	s_nop 0
	global_store_dwordx4 v236, v[32:35], s[22:23] offset:0
	v_lshlrev_b32_e32 v240, 16, v182
	v_and_b32_e32 v244, 0xffff0000, v182
	v_sub_f32_e32 v240, v240, v238
	v_sub_f32_e32 v244, v244, v238
	v_mul_f32_e32 v240, v240, v239
	v_mul_f32_e32 v244, v244, v239
	v_fma_f32 v240, v138, v240, v154
	v_fma_f32 v244, v139, v244, v155
	v_lshlrev_b32_e32 v241, 16, v190
	v_and_b32_e32 v245, 0xffff0000, v190
	v_lshlrev_b32_e32 v243, 16, v198
	v_and_b32_e32 v246, 0xffff0000, v198
	v_cndmask_b32_e32 v243, v243, v210, vcc
	v_cndmask_b32_e32 v246, v246, v211, vcc
	v_sub_f32_e32 v243, v243, v241
	v_sub_f32_e32 v246, v246, v245
	v_fmac_f32_e32 v241, v170, v243
	v_fmac_f32_e32 v245, v171, v246
	v_fmac_f32_e32 v240, v234, v241
	v_fmac_f32_e32 v244, v234, v245
	v_mul_f32_e32 v40, v40, v240
	v_mul_f32_e32 v41, v41, v244
	v_lshlrev_b32_e32 v240, 16, v183
	v_and_b32_e32 v244, 0xffff0000, v183
	v_sub_f32_e32 v240, v240, v238
	v_sub_f32_e32 v244, v244, v238
	v_mul_f32_e32 v240, v240, v239
	v_mul_f32_e32 v244, v244, v239
	v_fma_f32 v240, v140, v240, v156
	v_fma_f32 v244, v141, v244, v157
	v_lshlrev_b32_e32 v241, 16, v191
	v_and_b32_e32 v245, 0xffff0000, v191
	v_lshlrev_b32_e32 v243, 16, v199
	v_and_b32_e32 v246, 0xffff0000, v199
	v_cndmask_b32_e32 v243, v243, v212, vcc
	v_cndmask_b32_e32 v246, v246, v213, vcc
	v_sub_f32_e32 v243, v243, v241
	v_sub_f32_e32 v246, v246, v245
	v_fmac_f32_e32 v241, v172, v243
	v_fmac_f32_e32 v245, v173, v246
	v_fmac_f32_e32 v240, v234, v241
	v_fmac_f32_e32 v244, v234, v245
	v_mul_f32_e32 v42, v42, v240
	v_mul_f32_e32 v43, v43, v244
	v_lshlrev_b32_e32 v240, 16, v184
	v_and_b32_e32 v244, 0xffff0000, v184
	v_sub_f32_e32 v240, v240, v238
	v_sub_f32_e32 v244, v244, v238
	v_mul_f32_e32 v240, v240, v239
	v_mul_f32_e32 v244, v244, v239
	v_fma_f32 v240, v142, v240, v158
	v_fma_f32 v244, v143, v244, v159
	v_lshlrev_b32_e32 v241, 16, v192
	v_and_b32_e32 v245, 0xffff0000, v192
	v_lshlrev_b32_e32 v243, 16, v200
	v_and_b32_e32 v246, 0xffff0000, v200
	v_cndmask_b32_e32 v243, v243, v214, vcc
	v_cndmask_b32_e32 v246, v246, v215, vcc
	v_sub_f32_e32 v243, v243, v241
	v_sub_f32_e32 v246, v246, v245
	v_fmac_f32_e32 v241, v174, v243
	v_fmac_f32_e32 v245, v175, v246
	v_fmac_f32_e32 v240, v234, v241
	v_fmac_f32_e32 v244, v234, v245
	v_mul_f32_e32 v44, v44, v240
	v_mul_f32_e32 v45, v45, v244
	v_lshlrev_b32_e32 v240, 16, v185
	v_and_b32_e32 v244, 0xffff0000, v185
	v_sub_f32_e32 v240, v240, v238
	v_sub_f32_e32 v244, v244, v238
	v_mul_f32_e32 v240, v240, v239
	v_mul_f32_e32 v244, v244, v239
	v_fma_f32 v240, v144, v240, v160
	v_fma_f32 v244, v145, v244, v161
	v_lshlrev_b32_e32 v241, 16, v193
	v_and_b32_e32 v245, 0xffff0000, v193
	v_lshlrev_b32_e32 v243, 16, v201
	v_and_b32_e32 v246, 0xffff0000, v201
	v_cndmask_b32_e32 v243, v243, v216, vcc
	v_cndmask_b32_e32 v246, v246, v217, vcc
	v_sub_f32_e32 v243, v243, v241
	v_sub_f32_e32 v246, v246, v245
	v_fmac_f32_e32 v241, v176, v243
	v_fmac_f32_e32 v245, v177, v246
	v_fmac_f32_e32 v240, v234, v241
	v_fmac_f32_e32 v244, v234, v245
	v_mul_f32_e32 v46, v46, v240
	v_mul_f32_e32 v47, v47, v244
	v_cvt_pk_bf16_f32 v40, v40, v41
	v_cvt_pk_bf16_f32 v41, v42, v43
	v_cvt_pk_bf16_f32 v42, v44, v45
	v_cvt_pk_bf16_f32 v43, v46, v47
	v_add_u32_e32 v236, 0x8000, v230
	s_nop 0
	global_store_dwordx4 v236, v[40:43], s[22:23] offset:64
	v_add_u32_e32 v236, 0x10000, v230
	v_add_u32_e32 v237, 0x2c000, v231
	v_subrev_u32_e32 v240, 0x1600, v237
	global_load_dwordx4 v[178:181], v236, s[22:23] offset:0
	global_load_dwordx4 v[182:185], v236, s[22:23] offset:64
	global_load_dwordx4 v[186:189], v237, s[96:97] offset:0
	global_load_dwordx4 v[190:193], v237, s[96:97] offset:64
	global_load_dwordx4 v[194:197], v240, s[96:97] offset:0
	global_load_dwordx4 v[198:201], v240, s[96:97] offset:64
	v_add_u32_e32 v236, 0x1800, v232
	s_nop 0
	global_load_dword v234, v236, s[96:97] offset:0
	v_add_u32_e32 v237, 0x14000, v247
	global_load_dwordx4 v[202:205], v237, s[20:21] offset:0
	global_load_dwordx4 v[206:209], v237, s[20:21] offset:16
	global_load_dwordx4 v[210:213], v237, s[20:21] offset:128
	global_load_dwordx4 v[214:217], v237, s[20:21] offset:144
	s_waitcnt vmcnt(0)
; __device__ __forceinline__ float bf2f(u16 h) { return __uint_as_float(((unsigned)h) << 16); }
; template <int EPI> ...
;     ...
;         float o0 = bf2f(Y[(size_t)row * 1024 + 256 + ch0]);
;         float o1 = bf2f(Y[(size_t)row * 1024 + 256 + ch1]);
;         float mean = hsum32(o0 + o1) * (1.0f / 64.0f);
;         float d0 = o0 - mean, d1 = o1 - mean;
;         float var = hsum32(d0 * d0 + d1 * d1) * (1.0f / 64.0f);
;         float rstd = rsqrtf(var + 64e-5f);
;         float pv0 = bf2f(P[(size_t)row * 2816 + 256 + 1536 + ch0]);
;         float pv1 = bf2f(P[(size_t)row * 2816 + 256 + 1536 + ch1]);
;         float pp0 = prevP(p, P, row, 1536 + ch0), pp1 = prevP(p, P, row, 1536 + ch1);
;         float vv0 = pv0 + (pp0 - pv0) * mu0, vv1 = pv1 + (pp1 - pv1) * mu1;
;         float b = bs[((size_t)row * 12 + hh) * 4 + 2];
;         float y0 = (d0 * rstd * gg0 + gb0 + b * vv0) * acc0[i];
;         float y1 = (d1 * rstd * gg1 + gb1 + b * vv1) * acc1[i];
	v_lshlrev_b32_e32 v240, 16, v178
	v_and_b32_e32 v241, 0xffff0000, v178
	v_add_f32_e32 v244, v240, v241
	v_lshlrev_b32_e32 v240, 16, v179
	v_and_b32_e32 v241, 0xffff0000, v179
	v_add_f32_e32 v244, v244, v240
	v_add_f32_e32 v244, v244, v241
	v_lshlrev_b32_e32 v240, 16, v180
	v_and_b32_e32 v241, 0xffff0000, v180
	v_add_f32_e32 v244, v244, v240
	v_add_f32_e32 v244, v244, v241
	v_lshlrev_b32_e32 v240, 16, v181
	v_and_b32_e32 v241, 0xffff0000, v181
	v_add_f32_e32 v244, v244, v240
	v_add_f32_e32 v244, v244, v241
	v_lshlrev_b32_e32 v240, 16, v182
	v_and_b32_e32 v241, 0xffff0000, v182
	v_add_f32_e32 v244, v244, v240
	v_add_f32_e32 v244, v244, v241
	v_lshlrev_b32_e32 v240, 16, v183
	v_and_b32_e32 v241, 0xffff0000, v183
	v_add_f32_e32 v244, v244, v240
	v_add_f32_e32 v244, v244, v241
	v_lshlrev_b32_e32 v240, 16, v184
	v_and_b32_e32 v241, 0xffff0000, v184
	v_add_f32_e32 v244, v244, v240
	v_add_f32_e32 v244, v244, v241
	v_lshlrev_b32_e32 v240, 16, v185
	v_and_b32_e32 v241, 0xffff0000, v185
	v_add_f32_e32 v244, v244, v240
	v_add_f32_e32 v244, v244, v241
	v_mov_b32_e32 v240, v244
	s_nop 1
	v_permlane16_swap_b32_e32 v240, v244
	v_add_f32_e32 v244, v244, v240
	v_mov_b32_e32 v240, v244
	s_nop 1
	v_permlane32_swap_b32_e32 v240, v244
	v_add_f32_e32 v244, v244, v240
	v_mul_f32_e32 v238, 0x3c800000, v244
	v_lshlrev_b32_e32 v240, 16, v178
	v_and_b32_e32 v241, 0xffff0000, v178
	v_sub_f32_e32 v240, v240, v238
	v_sub_f32_e32 v241, v241, v238
	v_mul_f32_e32 v245, v240, v240
	v_fmac_f32_e32 v245, v241, v241
	v_lshlrev_b32_e32 v240, 16, v179
	v_and_b32_e32 v241, 0xffff0000, v179
	v_sub_f32_e32 v240, v240, v238
	v_sub_f32_e32 v241, v241, v238
	v_fmac_f32_e32 v245, v240, v240
	v_fmac_f32_e32 v245, v241, v241
	v_lshlrev_b32_e32 v240, 16, v180
	v_and_b32_e32 v241, 0xffff0000, v180
	v_sub_f32_e32 v240, v240, v238
	v_sub_f32_e32 v241, v241, v238
	v_fmac_f32_e32 v245, v240, v240
	v_fmac_f32_e32 v245, v241, v241
	v_lshlrev_b32_e32 v240, 16, v181
	v_and_b32_e32 v241, 0xffff0000, v181
	v_sub_f32_e32 v240, v240, v238
	v_sub_f32_e32 v241, v241, v238
	v_fmac_f32_e32 v245, v240, v240
	v_fmac_f32_e32 v245, v241, v241
	v_lshlrev_b32_e32 v240, 16, v182
	v_and_b32_e32 v241, 0xffff0000, v182
	v_sub_f32_e32 v240, v240, v238
	v_sub_f32_e32 v241, v241, v238
	v_fmac_f32_e32 v245, v240, v240
	v_fmac_f32_e32 v245, v241, v241
	v_lshlrev_b32_e32 v240, 16, v183
	v_and_b32_e32 v241, 0xffff0000, v183
	v_sub_f32_e32 v240, v240, v238
	v_sub_f32_e32 v241, v241, v238
	v_fmac_f32_e32 v245, v240, v240
	v_fmac_f32_e32 v245, v241, v241
	v_lshlrev_b32_e32 v240, 16, v184
	v_and_b32_e32 v241, 0xffff0000, v184
	v_sub_f32_e32 v240, v240, v238
	v_sub_f32_e32 v241, v241, v238
	v_fmac_f32_e32 v245, v240, v240
	v_fmac_f32_e32 v245, v241, v241
	v_lshlrev_b32_e32 v240, 16, v185
	v_and_b32_e32 v241, 0xffff0000, v185
	v_sub_f32_e32 v240, v240, v238
	v_sub_f32_e32 v241, v241, v238
	v_fmac_f32_e32 v245, v240, v240
	v_fmac_f32_e32 v245, v241, v241
	v_mov_b32_e32 v240, v245
	s_nop 1
	v_permlane16_swap_b32_e32 v240, v245
	v_add_f32_e32 v245, v245, v240
	v_mov_b32_e32 v240, v245
	s_nop 1
	v_permlane32_swap_b32_e32 v240, v245
	v_add_f32_e32 v245, v245, v240
	v_mov_b32_e32 v240, 0x3a27c5ac
	v_fmamk_f32 v245, v245, 0x3c800000, v240
	v_rsq_f32_e32 v239, v245
	v_and_b32_e32 v240, 3, v248
	v_cmp_eq_u32_e32 vcc, 0, v240
	s_nop 1
	v_lshlrev_b32_e32 v240, 16, v178
	v_and_b32_e32 v244, 0xffff0000, v178
	v_sub_f32_e32 v240, v240, v238
	v_sub_f32_e32 v244, v244, v238
	v_mul_f32_e32 v240, v240, v239
	v_mul_f32_e32 v244, v244, v239
	v_fma_f32 v240, v130, v240, v146
	v_fma_f32 v244, v131, v244, v147
	v_lshlrev_b32_e32 v241, 16, v186
	v_and_b32_e32 v245, 0xffff0000, v186
	v_lshlrev_b32_e32 v243, 16, v194
	v_and_b32_e32 v246, 0xffff0000, v194
	v_cndmask_b32_e32 v243, v243, v202, vcc
	v_cndmask_b32_e32 v246, v246, v203, vcc
	v_sub_f32_e32 v243, v243, v241
	v_sub_f32_e32 v246, v246, v245
	v_fmac_f32_e32 v241, v162, v243
	v_fmac_f32_e32 v245, v163, v246
	v_fmac_f32_e32 v240, v234, v241
	v_fmac_f32_e32 v244, v234, v245
	v_mul_f32_e32 v64, v64, v240
	v_mul_f32_e32 v65, v65, v244
	v_lshlrev_b32_e32 v240, 16, v179
	v_and_b32_e32 v244, 0xffff0000, v179
	v_sub_f32_e32 v240, v240, v238
	v_sub_f32_e32 v244, v244, v238
	v_mul_f32_e32 v240, v240, v239
	v_mul_f32_e32 v244, v244, v239
	v_fma_f32 v240, v132, v240, v148
	v_fma_f32 v244, v133, v244, v149
	v_lshlrev_b32_e32 v241, 16, v187
	v_and_b32_e32 v245, 0xffff0000, v187
	v_lshlrev_b32_e32 v243, 16, v195
	v_and_b32_e32 v246, 0xffff0000, v195
	v_cndmask_b32_e32 v243, v243, v204, vcc
	v_cndmask_b32_e32 v246, v246, v205, vcc
	v_sub_f32_e32 v243, v243, v241
	v_sub_f32_e32 v246, v246, v245
	v_fmac_f32_e32 v241, v164, v243
	v_fmac_f32_e32 v245, v165, v246
	v_fmac_f32_e32 v240, v234, v241
	v_fmac_f32_e32 v244, v234, v245
	v_mul_f32_e32 v66, v66, v240
	v_mul_f32_e32 v67, v67, v244
	v_lshlrev_b32_e32 v240, 16, v180
	v_and_b32_e32 v244, 0xffff0000, v180
	v_sub_f32_e32 v240, v240, v238
	v_sub_f32_e32 v244, v244, v238
	v_mul_f32_e32 v240, v240, v239
	v_mul_f32_e32 v244, v244, v239
	v_fma_f32 v240, v134, v240, v150
	v_fma_f32 v244, v135, v244, v151
	v_lshlrev_b32_e32 v241, 16, v188
	v_and_b32_e32 v245, 0xffff0000, v188
	v_lshlrev_b32_e32 v243, 16, v196
	v_and_b32_e32 v246, 0xffff0000, v196
	v_cndmask_b32_e32 v243, v243, v206, vcc
	v_cndmask_b32_e32 v246, v246, v207, vcc
	v_sub_f32_e32 v243, v243, v241
	v_sub_f32_e32 v246, v246, v245
	v_fmac_f32_e32 v241, v166, v243
	v_fmac_f32_e32 v245, v167, v246
	v_fmac_f32_e32 v240, v234, v241
	v_fmac_f32_e32 v244, v234, v245
	v_mul_f32_e32 v68, v68, v240
	v_mul_f32_e32 v69, v69, v244
	v_lshlrev_b32_e32 v240, 16, v181
	v_and_b32_e32 v244, 0xffff0000, v181
	v_sub_f32_e32 v240, v240, v238
; __device__ __forceinline__ float bf2f(u16 h) { return __uint_as_float(((unsigned)h) << 16); }
; template <int EPI> ...
;     ...
;         float pv0 = bf2f(P[(size_t)row * 2816 + 256 + 1536 + ch0]);
;         float pv1 = bf2f(P[(size_t)row * 2816 + 256 + 1536 + ch1]);
;         float pp0 = prevP(p, P, row, 1536 + ch0), pp1 = prevP(p, P, row, 1536 + ch1);
;         float vv0 = pv0 + (pp0 - pv0) * mu0, vv1 = pv1 + (pp1 - pv1) * mu1;
;         float b = bs[((size_t)row * 12 + hh) * 4 + 2];
;         float y0 = (d0 * rstd * gg0 + gb0 + b * vv0) * acc0[i];
;         float y1 = (d1 * rstd * gg1 + gb1 + b * vv1) * acc1[i];
;         Y[(size_t)row * 1024 + 256 + ch0] = f2bf(y0);
;         Y[(size_t)row * 1024 + 256 + ch1] = f2bf(y1);
;       }
	v_sub_f32_e32 v244, v244, v238
	v_mul_f32_e32 v240, v240, v239
	v_mul_f32_e32 v244, v244, v239
	v_fma_f32 v240, v136, v240, v152
	v_fma_f32 v244, v137, v244, v153
	v_lshlrev_b32_e32 v241, 16, v189
	v_and_b32_e32 v245, 0xffff0000, v189
	v_lshlrev_b32_e32 v243, 16, v197
	v_and_b32_e32 v246, 0xffff0000, v197
	v_cndmask_b32_e32 v243, v243, v208, vcc
	v_cndmask_b32_e32 v246, v246, v209, vcc
	v_sub_f32_e32 v243, v243, v241
	v_sub_f32_e32 v246, v246, v245
	v_fmac_f32_e32 v241, v168, v243
	v_fmac_f32_e32 v245, v169, v246
	v_fmac_f32_e32 v240, v234, v241
	v_fmac_f32_e32 v244, v234, v245
	v_mul_f32_e32 v70, v70, v240
	v_mul_f32_e32 v71, v71, v244
	v_cvt_pk_bf16_f32 v64, v64, v65
	v_cvt_pk_bf16_f32 v65, v66, v67
	v_cvt_pk_bf16_f32 v66, v68, v69
	v_cvt_pk_bf16_f32 v67, v70, v71
	v_add_u32_e32 v236, 0x10000, v230
	s_nop 0
	global_store_dwordx4 v236, v[64:67], s[22:23] offset:0
	v_lshlrev_b32_e32 v240, 16, v182
	v_and_b32_e32 v244, 0xffff0000, v182
	v_sub_f32_e32 v240, v240, v238
	v_sub_f32_e32 v244, v244, v238
	v_mul_f32_e32 v240, v240, v239
	v_mul_f32_e32 v244, v244, v239
	v_fma_f32 v240, v138, v240, v154
	v_fma_f32 v244, v139, v244, v155
	v_lshlrev_b32_e32 v241, 16, v190
	v_and_b32_e32 v245, 0xffff0000, v190
	v_lshlrev_b32_e32 v243, 16, v198
	v_and_b32_e32 v246, 0xffff0000, v198
	v_cndmask_b32_e32 v243, v243, v210, vcc
	v_cndmask_b32_e32 v246, v246, v211, vcc
	v_sub_f32_e32 v243, v243, v241
	v_sub_f32_e32 v246, v246, v245
	v_fmac_f32_e32 v241, v170, v243
	v_fmac_f32_e32 v245, v171, v246
	v_fmac_f32_e32 v240, v234, v241
	v_fmac_f32_e32 v244, v234, v245
	v_mul_f32_e32 v72, v72, v240
	v_mul_f32_e32 v73, v73, v244
	v_lshlrev_b32_e32 v240, 16, v183
	v_and_b32_e32 v244, 0xffff0000, v183
	v_sub_f32_e32 v240, v240, v238
	v_sub_f32_e32 v244, v244, v238
	v_mul_f32_e32 v240, v240, v239
	v_mul_f32_e32 v244, v244, v239
	v_fma_f32 v240, v140, v240, v156
	v_fma_f32 v244, v141, v244, v157
	v_lshlrev_b32_e32 v241, 16, v191
	v_and_b32_e32 v245, 0xffff0000, v191
	v_lshlrev_b32_e32 v243, 16, v199
	v_and_b32_e32 v246, 0xffff0000, v199
	v_cndmask_b32_e32 v243, v243, v212, vcc
	v_cndmask_b32_e32 v246, v246, v213, vcc
	v_sub_f32_e32 v243, v243, v241
	v_sub_f32_e32 v246, v246, v245
	v_fmac_f32_e32 v241, v172, v243
	v_fmac_f32_e32 v245, v173, v246
	v_fmac_f32_e32 v240, v234, v241
	v_fmac_f32_e32 v244, v234, v245
	v_mul_f32_e32 v74, v74, v240
	v_mul_f32_e32 v75, v75, v244
	v_lshlrev_b32_e32 v240, 16, v184
	v_and_b32_e32 v244, 0xffff0000, v184
	v_sub_f32_e32 v240, v240, v238
	v_sub_f32_e32 v244, v244, v238
	v_mul_f32_e32 v240, v240, v239
	v_mul_f32_e32 v244, v244, v239
	v_fma_f32 v240, v142, v240, v158
	v_fma_f32 v244, v143, v244, v159
	v_lshlrev_b32_e32 v241, 16, v192
	v_and_b32_e32 v245, 0xffff0000, v192
	v_lshlrev_b32_e32 v243, 16, v200
	v_and_b32_e32 v246, 0xffff0000, v200
	v_cndmask_b32_e32 v243, v243, v214, vcc
	v_cndmask_b32_e32 v246, v246, v215, vcc
	v_sub_f32_e32 v243, v243, v241
	v_sub_f32_e32 v246, v246, v245
	v_fmac_f32_e32 v241, v174, v243
	v_fmac_f32_e32 v245, v175, v246
	v_fmac_f32_e32 v240, v234, v241
	v_fmac_f32_e32 v244, v234, v245
	v_mul_f32_e32 v76, v76, v240
	v_mul_f32_e32 v77, v77, v244
	v_lshlrev_b32_e32 v240, 16, v185
	v_and_b32_e32 v244, 0xffff0000, v185
	v_sub_f32_e32 v240, v240, v238
	v_sub_f32_e32 v244, v244, v238
	v_mul_f32_e32 v240, v240, v239
	v_mul_f32_e32 v244, v244, v239
	v_fma_f32 v240, v144, v240, v160
	v_fma_f32 v244, v145, v244, v161
	v_lshlrev_b32_e32 v241, 16, v193
	v_and_b32_e32 v245, 0xffff0000, v193
	v_lshlrev_b32_e32 v243, 16, v201
	v_and_b32_e32 v246, 0xffff0000, v201
	v_cndmask_b32_e32 v243, v243, v216, vcc
	v_cndmask_b32_e32 v246, v246, v217, vcc
	v_sub_f32_e32 v243, v243, v241
	v_sub_f32_e32 v246, v246, v245
	v_fmac_f32_e32 v241, v176, v243
	v_fmac_f32_e32 v245, v177, v246
	v_fmac_f32_e32 v240, v234, v241
	v_fmac_f32_e32 v244, v234, v245
	v_mul_f32_e32 v78, v78, v240
	v_mul_f32_e32 v79, v79, v244
	v_cvt_pk_bf16_f32 v72, v72, v73
	v_cvt_pk_bf16_f32 v73, v74, v75
	v_cvt_pk_bf16_f32 v74, v76, v77
	v_cvt_pk_bf16_f32 v75, v78, v79
	v_add_u32_e32 v236, 0x10000, v230
	s_nop 0
	global_store_dwordx4 v236, v[72:75], s[22:23] offset:64
	v_add_u32_e32 v236, 0x18000, v230
	v_add_u32_e32 v237, 0x42000, v231
	v_subrev_u32_e32 v240, 0x1600, v237
	global_load_dwordx4 v[178:181], v236, s[22:23] offset:0
	global_load_dwordx4 v[182:185], v236, s[22:23] offset:64
	global_load_dwordx4 v[186:189], v237, s[96:97] offset:0
	global_load_dwordx4 v[190:193], v237, s[96:97] offset:64
	global_load_dwordx4 v[194:197], v240, s[96:97] offset:0
	global_load_dwordx4 v[198:201], v240, s[96:97] offset:64
	v_add_u32_e32 v236, 0x2400, v232
	s_nop 0
	global_load_dword v234, v236, s[96:97] offset:0
	v_add_u32_e32 v237, 0x1e000, v247
	global_load_dwordx4 v[202:205], v237, s[20:21] offset:0
	global_load_dwordx4 v[206:209], v237, s[20:21] offset:16
	global_load_dwordx4 v[210:213], v237, s[20:21] offset:128
	global_load_dwordx4 v[214:217], v237, s[20:21] offset:144
	s_waitcnt vmcnt(0)
; __device__ __forceinline__ float bf2f(u16 h) { return __uint_as_float(((unsigned)h) << 16); }
; template <int EPI> ...
;     ...
;         float o0 = bf2f(Y[(size_t)row * 1024 + 256 + ch0]);
;         float o1 = bf2f(Y[(size_t)row * 1024 + 256 + ch1]);
;         float mean = hsum32(o0 + o1) * (1.0f / 64.0f);
;         float d0 = o0 - mean, d1 = o1 - mean;
;         float var = hsum32(d0 * d0 + d1 * d1) * (1.0f / 64.0f);
;         float rstd = rsqrtf(var + 64e-5f);
;         float pv0 = bf2f(P[(size_t)row * 2816 + 256 + 1536 + ch0]);
;         float pv1 = bf2f(P[(size_t)row * 2816 + 256 + 1536 + ch1]);
;         float pp0 = prevP(p, P, row, 1536 + ch0), pp1 = prevP(p, P, row, 1536 + ch1);
;         float vv0 = pv0 + (pp0 - pv0) * mu0, vv1 = pv1 + (pp1 - pv1) * mu1;
;         float b = bs[((size_t)row * 12 + hh) * 4 + 2];
;         float y0 = (d0 * rstd * gg0 + gb0 + b * vv0) * acc0[i];
;         float y1 = (d1 * rstd * gg1 + gb1 + b * vv1) * acc1[i];
	v_lshlrev_b32_e32 v240, 16, v178
	v_and_b32_e32 v241, 0xffff0000, v178
	v_add_f32_e32 v244, v240, v241
	v_lshlrev_b32_e32 v240, 16, v179
	v_and_b32_e32 v241, 0xffff0000, v179
	v_add_f32_e32 v244, v244, v240
	v_add_f32_e32 v244, v244, v241
	v_lshlrev_b32_e32 v240, 16, v180
	v_and_b32_e32 v241, 0xffff0000, v180
	v_add_f32_e32 v244, v244, v240
	v_add_f32_e32 v244, v244, v241
	v_lshlrev_b32_e32 v240, 16, v181
	v_and_b32_e32 v241, 0xffff0000, v181
	v_add_f32_e32 v244, v244, v240
	v_add_f32_e32 v244, v244, v241
	v_lshlrev_b32_e32 v240, 16, v182
	v_and_b32_e32 v241, 0xffff0000, v182
	v_add_f32_e32 v244, v244, v240
	v_add_f32_e32 v244, v244, v241
	v_lshlrev_b32_e32 v240, 16, v183
	v_and_b32_e32 v241, 0xffff0000, v183
	v_add_f32_e32 v244, v244, v240
	v_add_f32_e32 v244, v244, v241
	v_lshlrev_b32_e32 v240, 16, v184
	v_and_b32_e32 v241, 0xffff0000, v184
	v_add_f32_e32 v244, v244, v240
	v_add_f32_e32 v244, v244, v241
	v_lshlrev_b32_e32 v240, 16, v185
	v_and_b32_e32 v241, 0xffff0000, v185
	v_add_f32_e32 v244, v244, v240
	v_add_f32_e32 v244, v244, v241
	v_mov_b32_e32 v240, v244
	s_nop 1
	v_permlane16_swap_b32_e32 v240, v244
	v_add_f32_e32 v244, v244, v240
	v_mov_b32_e32 v240, v244
	s_nop 1
	v_permlane32_swap_b32_e32 v240, v244
	v_add_f32_e32 v244, v244, v240
	v_mul_f32_e32 v238, 0x3c800000, v244
	v_lshlrev_b32_e32 v240, 16, v178
	v_and_b32_e32 v241, 0xffff0000, v178
	v_sub_f32_e32 v240, v240, v238
	v_sub_f32_e32 v241, v241, v238
	v_mul_f32_e32 v245, v240, v240
	v_fmac_f32_e32 v245, v241, v241
	v_lshlrev_b32_e32 v240, 16, v179
	v_and_b32_e32 v241, 0xffff0000, v179
	v_sub_f32_e32 v240, v240, v238
	v_sub_f32_e32 v241, v241, v238
	v_fmac_f32_e32 v245, v240, v240
	v_fmac_f32_e32 v245, v241, v241
	v_lshlrev_b32_e32 v240, 16, v180
	v_and_b32_e32 v241, 0xffff0000, v180
	v_sub_f32_e32 v240, v240, v238
	v_sub_f32_e32 v241, v241, v238
	v_fmac_f32_e32 v245, v240, v240
	v_fmac_f32_e32 v245, v241, v241
	v_lshlrev_b32_e32 v240, 16, v181
	v_and_b32_e32 v241, 0xffff0000, v181
	v_sub_f32_e32 v240, v240, v238
	v_sub_f32_e32 v241, v241, v238
	v_fmac_f32_e32 v245, v240, v240
	v_fmac_f32_e32 v245, v241, v241
	v_lshlrev_b32_e32 v240, 16, v182
	v_and_b32_e32 v241, 0xffff0000, v182
	v_sub_f32_e32 v240, v240, v238
	v_sub_f32_e32 v241, v241, v238
	v_fmac_f32_e32 v245, v240, v240
	v_fmac_f32_e32 v245, v241, v241
	v_lshlrev_b32_e32 v240, 16, v183
	v_and_b32_e32 v241, 0xffff0000, v183
	v_sub_f32_e32 v240, v240, v238
	v_sub_f32_e32 v241, v241, v238
	v_fmac_f32_e32 v245, v240, v240
	v_fmac_f32_e32 v245, v241, v241
	v_lshlrev_b32_e32 v240, 16, v184
	v_and_b32_e32 v241, 0xffff0000, v184
	v_sub_f32_e32 v240, v240, v238
	v_sub_f32_e32 v241, v241, v238
	v_fmac_f32_e32 v245, v240, v240
	v_fmac_f32_e32 v245, v241, v241
	v_lshlrev_b32_e32 v240, 16, v185
	v_and_b32_e32 v241, 0xffff0000, v185
	v_sub_f32_e32 v240, v240, v238
	v_sub_f32_e32 v241, v241, v238
	v_fmac_f32_e32 v245, v240, v240
	v_fmac_f32_e32 v245, v241, v241
	v_mov_b32_e32 v240, v245
	s_nop 1
	v_permlane16_swap_b32_e32 v240, v245
	v_add_f32_e32 v245, v245, v240
	v_mov_b32_e32 v240, v245
	s_nop 1
	v_permlane32_swap_b32_e32 v240, v245
	v_add_f32_e32 v245, v245, v240
	v_mov_b32_e32 v240, 0x3a27c5ac
	v_fmamk_f32 v245, v245, 0x3c800000, v240
	v_rsq_f32_e32 v239, v245
	v_and_b32_e32 v240, 3, v248
	v_cmp_eq_u32_e32 vcc, 0, v240
	s_nop 1
	v_lshlrev_b32_e32 v240, 16, v178
	v_and_b32_e32 v244, 0xffff0000, v178
	v_sub_f32_e32 v240, v240, v238
	v_sub_f32_e32 v244, v244, v238
	v_mul_f32_e32 v240, v240, v239
	v_mul_f32_e32 v244, v244, v239
	v_fma_f32 v240, v130, v240, v146
	v_fma_f32 v244, v131, v244, v147
	v_lshlrev_b32_e32 v241, 16, v186
	v_and_b32_e32 v245, 0xffff0000, v186
	v_lshlrev_b32_e32 v243, 16, v194
	v_and_b32_e32 v246, 0xffff0000, v194
	v_cndmask_b32_e32 v243, v243, v202, vcc
	v_cndmask_b32_e32 v246, v246, v203, vcc
	v_sub_f32_e32 v243, v243, v241
	v_sub_f32_e32 v246, v246, v245
	v_fmac_f32_e32 v241, v162, v243
	v_fmac_f32_e32 v245, v163, v246
	v_fmac_f32_e32 v240, v234, v241
	v_fmac_f32_e32 v244, v234, v245
	v_mul_f32_e32 v96, v96, v240
	v_mul_f32_e32 v97, v97, v244
	v_lshlrev_b32_e32 v240, 16, v179
	v_and_b32_e32 v244, 0xffff0000, v179
	v_sub_f32_e32 v240, v240, v238
	v_sub_f32_e32 v244, v244, v238
	v_mul_f32_e32 v240, v240, v239
	v_mul_f32_e32 v244, v244, v239
	v_fma_f32 v240, v132, v240, v148
	v_fma_f32 v244, v133, v244, v149
	v_lshlrev_b32_e32 v241, 16, v187
	v_and_b32_e32 v245, 0xffff0000, v187
	v_lshlrev_b32_e32 v243, 16, v195
	v_and_b32_e32 v246, 0xffff0000, v195
	v_cndmask_b32_e32 v243, v243, v204, vcc
	v_cndmask_b32_e32 v246, v246, v205, vcc
	v_sub_f32_e32 v243, v243, v241
	v_sub_f32_e32 v246, v246, v245
	v_fmac_f32_e32 v241, v164, v243
	v_fmac_f32_e32 v245, v165, v246
	v_fmac_f32_e32 v240, v234, v241
	v_fmac_f32_e32 v244, v234, v245
	v_mul_f32_e32 v98, v98, v240
	v_mul_f32_e32 v99, v99, v244
	v_lshlrev_b32_e32 v240, 16, v180
	v_and_b32_e32 v244, 0xffff0000, v180
	v_sub_f32_e32 v240, v240, v238
	v_sub_f32_e32 v244, v244, v238
	v_mul_f32_e32 v240, v240, v239
	v_mul_f32_e32 v244, v244, v239
	v_fma_f32 v240, v134, v240, v150
	v_fma_f32 v244, v135, v244, v151
	v_lshlrev_b32_e32 v241, 16, v188
	v_and_b32_e32 v245, 0xffff0000, v188
	v_lshlrev_b32_e32 v243, 16, v196
	v_and_b32_e32 v246, 0xffff0000, v196
	v_cndmask_b32_e32 v243, v243, v206, vcc
	v_cndmask_b32_e32 v246, v246, v207, vcc
	v_sub_f32_e32 v243, v243, v241
	v_sub_f32_e32 v246, v246, v245
	v_fmac_f32_e32 v241, v166, v243
	v_fmac_f32_e32 v245, v167, v246
	v_fmac_f32_e32 v240, v234, v241
	v_fmac_f32_e32 v244, v234, v245
	v_mul_f32_e32 v100, v100, v240
	v_mul_f32_e32 v101, v101, v244
	v_lshlrev_b32_e32 v240, 16, v181
	v_and_b32_e32 v244, 0xffff0000, v181
; __device__ __forceinline__ float bf2f(u16 h) { return __uint_as_float(((unsigned)h) << 16); }
; template <int EPI> ...
;     ...
;       const float gg0 = p.in[20][ch0], gg1 = p.in[20][ch1];
;       const float gb0 = p.in[21][ch0], gb1 = p.in[21][ch1];
;       const float mu0 = p.in[11][1536 + ch0], mu1 = p.in[11][1536 + ch1];
;     ...
;         float pv0 = bf2f(P[(size_t)row * 2816 + 256 + 1536 + ch0]);
;         float pv1 = bf2f(P[(size_t)row * 2816 + 256 + 1536 + ch1]);
;         float pp0 = prevP(p, P, row, 1536 + ch0), pp1 = prevP(p, P, row, 1536 + ch1);
;         float vv0 = pv0 + (pp0 - pv0) * mu0, vv1 = pv1 + (pp1 - pv1) * mu1;
;         float b = bs[((size_t)row * 12 + hh) * 4 + 2];
;         float y0 = (d0 * rstd * gg0 + gb0 + b * vv0) * acc0[i];
;         float y1 = (d1 * rstd * gg1 + gb1 + b * vv1) * acc1[i];
;         Y[(size_t)row * 1024 + 256 + ch0] = f2bf(y0);
;         Y[(size_t)row * 1024 + 256 + ch1] = f2bf(y1);
;       }
	v_sub_f32_e32 v240, v240, v238
	v_sub_f32_e32 v244, v244, v238
	v_mul_f32_e32 v240, v240, v239
	v_mul_f32_e32 v244, v244, v239
	v_fma_f32 v240, v136, v240, v152
	v_fma_f32 v244, v137, v244, v153
	v_lshlrev_b32_e32 v241, 16, v189
	v_and_b32_e32 v245, 0xffff0000, v189
	v_lshlrev_b32_e32 v243, 16, v197
	v_and_b32_e32 v246, 0xffff0000, v197
	v_cndmask_b32_e32 v243, v243, v208, vcc
	v_cndmask_b32_e32 v246, v246, v209, vcc
	v_sub_f32_e32 v243, v243, v241
	v_sub_f32_e32 v246, v246, v245
	v_fmac_f32_e32 v241, v168, v243
	v_fmac_f32_e32 v245, v169, v246
	v_fmac_f32_e32 v240, v234, v241
	v_fmac_f32_e32 v244, v234, v245
	v_mul_f32_e32 v102, v102, v240
	v_mul_f32_e32 v103, v103, v244
	v_cvt_pk_bf16_f32 v96, v96, v97
	v_cvt_pk_bf16_f32 v97, v98, v99
	v_cvt_pk_bf16_f32 v98, v100, v101
	v_cvt_pk_bf16_f32 v99, v102, v103
	v_add_u32_e32 v236, 0x18000, v230
	s_nop 0
	global_store_dwordx4 v236, v[96:99], s[22:23] offset:0
	v_lshlrev_b32_e32 v240, 16, v182
	v_and_b32_e32 v244, 0xffff0000, v182
	v_sub_f32_e32 v240, v240, v238
	v_sub_f32_e32 v244, v244, v238
	v_mul_f32_e32 v240, v240, v239
	v_mul_f32_e32 v244, v244, v239
	v_fma_f32 v240, v138, v240, v154
	v_fma_f32 v244, v139, v244, v155
	v_lshlrev_b32_e32 v241, 16, v190
	v_and_b32_e32 v245, 0xffff0000, v190
	v_lshlrev_b32_e32 v243, 16, v198
	v_and_b32_e32 v246, 0xffff0000, v198
	v_cndmask_b32_e32 v243, v243, v210, vcc
	v_cndmask_b32_e32 v246, v246, v211, vcc
	v_sub_f32_e32 v243, v243, v241
	v_sub_f32_e32 v246, v246, v245
	v_fmac_f32_e32 v241, v170, v243
	v_fmac_f32_e32 v245, v171, v246
	v_fmac_f32_e32 v240, v234, v241
	v_fmac_f32_e32 v244, v234, v245
	v_mul_f32_e32 v104, v104, v240
	v_mul_f32_e32 v105, v105, v244
	v_lshlrev_b32_e32 v240, 16, v183
	v_and_b32_e32 v244, 0xffff0000, v183
	v_sub_f32_e32 v240, v240, v238
	v_sub_f32_e32 v244, v244, v238
	v_mul_f32_e32 v240, v240, v239
	v_mul_f32_e32 v244, v244, v239
	v_fma_f32 v240, v140, v240, v156
	v_fma_f32 v244, v141, v244, v157
	v_lshlrev_b32_e32 v241, 16, v191
	v_and_b32_e32 v245, 0xffff0000, v191
	v_lshlrev_b32_e32 v243, 16, v199
	v_and_b32_e32 v246, 0xffff0000, v199
	v_cndmask_b32_e32 v243, v243, v212, vcc
	v_cndmask_b32_e32 v246, v246, v213, vcc
	v_sub_f32_e32 v243, v243, v241
	v_sub_f32_e32 v246, v246, v245
	v_fmac_f32_e32 v241, v172, v243
	v_fmac_f32_e32 v245, v173, v246
	v_fmac_f32_e32 v240, v234, v241
	v_fmac_f32_e32 v244, v234, v245
	v_mul_f32_e32 v106, v106, v240
	v_mul_f32_e32 v107, v107, v244
	v_lshlrev_b32_e32 v240, 16, v184
	v_and_b32_e32 v244, 0xffff0000, v184
	v_sub_f32_e32 v240, v240, v238
	v_sub_f32_e32 v244, v244, v238
	v_mul_f32_e32 v240, v240, v239
	v_mul_f32_e32 v244, v244, v239
	v_fma_f32 v240, v142, v240, v158
	v_fma_f32 v244, v143, v244, v159
	v_lshlrev_b32_e32 v241, 16, v192
	v_and_b32_e32 v245, 0xffff0000, v192
	v_lshlrev_b32_e32 v243, 16, v200
	v_and_b32_e32 v246, 0xffff0000, v200
	v_cndmask_b32_e32 v243, v243, v214, vcc
	v_cndmask_b32_e32 v246, v246, v215, vcc
	v_sub_f32_e32 v243, v243, v241
	v_sub_f32_e32 v246, v246, v245
	v_fmac_f32_e32 v241, v174, v243
	v_fmac_f32_e32 v245, v175, v246
	v_fmac_f32_e32 v240, v234, v241
	v_fmac_f32_e32 v244, v234, v245
	v_mul_f32_e32 v108, v108, v240
	v_mul_f32_e32 v109, v109, v244
	v_lshlrev_b32_e32 v240, 16, v185
	v_and_b32_e32 v244, 0xffff0000, v185
	v_sub_f32_e32 v240, v240, v238
	v_sub_f32_e32 v244, v244, v238
	v_mul_f32_e32 v240, v240, v239
	v_mul_f32_e32 v244, v244, v239
	v_fma_f32 v240, v144, v240, v160
	v_fma_f32 v244, v145, v244, v161
	v_lshlrev_b32_e32 v241, 16, v193
	v_and_b32_e32 v245, 0xffff0000, v193
	v_lshlrev_b32_e32 v243, 16, v201
	v_and_b32_e32 v246, 0xffff0000, v201
	v_cndmask_b32_e32 v243, v243, v216, vcc
	v_cndmask_b32_e32 v246, v246, v217, vcc
	v_sub_f32_e32 v243, v243, v241
	v_sub_f32_e32 v246, v246, v245
	v_fmac_f32_e32 v241, v176, v243
	v_fmac_f32_e32 v245, v177, v246
	v_fmac_f32_e32 v240, v234, v241
	v_fmac_f32_e32 v244, v234, v245
	v_mul_f32_e32 v110, v110, v240
	v_mul_f32_e32 v111, v111, v244
	v_cvt_pk_bf16_f32 v104, v104, v105
	v_cvt_pk_bf16_f32 v105, v106, v107
	v_cvt_pk_bf16_f32 v106, v108, v109
	v_cvt_pk_bf16_f32 v107, v110, v111
	v_add_u32_e32 v236, 0x18000, v230
	s_nop 0
	global_store_dwordx4 v236, v[104:107], s[22:23] offset:64
	global_load_dwordx4 v[130:133], v233, s[2:3] offset:256
	global_load_dwordx4 v[134:137], v233, s[2:3] offset:272
	global_load_dwordx4 v[138:141], v233, s[2:3] offset:384
	global_load_dwordx4 v[142:145], v233, s[2:3] offset:400
	global_load_dwordx4 v[146:149], v233, s[16:17] offset:256
	global_load_dwordx4 v[150:153], v233, s[16:17] offset:272
	global_load_dwordx4 v[154:157], v233, s[16:17] offset:384
	global_load_dwordx4 v[158:161], v233, s[16:17] offset:400
	global_load_dwordx4 v[162:165], v233, s[0:1] offset:256
	global_load_dwordx4 v[166:169], v233, s[0:1] offset:272
	global_load_dwordx4 v[170:173], v233, s[0:1] offset:384
	global_load_dwordx4 v[174:177], v233, s[0:1] offset:400
	v_add_u32_e32 v236, 0x0, v230
	v_add_u32_e32 v237, 0x0, v231
	v_subrev_u32_e32 v240, 0x1600, v237
	global_load_dwordx4 v[178:181], v236, s[22:23] offset:128
	global_load_dwordx4 v[182:185], v236, s[22:23] offset:192
	global_load_dwordx4 v[186:189], v237, s[96:97] offset:128
	global_load_dwordx4 v[190:193], v237, s[96:97] offset:192
	global_load_dwordx4 v[194:197], v240, s[96:97] offset:128
	global_load_dwordx4 v[198:201], v240, s[96:97] offset:192
	v_add_u32_e32 v236, 0x0, v232
	s_nop 0
	global_load_dword v234, v236, s[96:97] offset:16
	v_add_u32_e32 v237, 0x0, v247
	global_load_dwordx4 v[202:205], v237, s[20:21] offset:256
	global_load_dwordx4 v[206:209], v237, s[20:21] offset:272
	global_load_dwordx4 v[210:213], v237, s[20:21] offset:384
	global_load_dwordx4 v[214:217], v237, s[20:21] offset:400
	s_waitcnt vmcnt(0)
; __device__ __forceinline__ float bf2f(u16 h) { return __uint_as_float(((unsigned)h) << 16); }
; template <int EPI> ...
;     ...
;         float o0 = bf2f(Y[(size_t)row * 1024 + 256 + ch0]);
;         float o1 = bf2f(Y[(size_t)row * 1024 + 256 + ch1]);
;         float mean = hsum32(o0 + o1) * (1.0f / 64.0f);
;         float d0 = o0 - mean, d1 = o1 - mean;
;         float var = hsum32(d0 * d0 + d1 * d1) * (1.0f / 64.0f);
;         float rstd = rsqrtf(var + 64e-5f);
;         float pv0 = bf2f(P[(size_t)row * 2816 + 256 + 1536 + ch0]);
;         float pv1 = bf2f(P[(size_t)row * 2816 + 256 + 1536 + ch1]);
;         float pp0 = prevP(p, P, row, 1536 + ch0), pp1 = prevP(p, P, row, 1536 + ch1);
;         float vv0 = pv0 + (pp0 - pv0) * mu0, vv1 = pv1 + (pp1 - pv1) * mu1;
;         float b = bs[((size_t)row * 12 + hh) * 4 + 2];
;         float y0 = (d0 * rstd * gg0 + gb0 + b * vv0) * acc0[i];
;         float y1 = (d1 * rstd * gg1 + gb1 + b * vv1) * acc1[i];
	v_lshlrev_b32_e32 v240, 16, v178
	v_and_b32_e32 v241, 0xffff0000, v178
	v_add_f32_e32 v244, v240, v241
	v_lshlrev_b32_e32 v240, 16, v179
	v_and_b32_e32 v241, 0xffff0000, v179
	v_add_f32_e32 v244, v244, v240
	v_add_f32_e32 v244, v244, v241
	v_lshlrev_b32_e32 v240, 16, v180
	v_and_b32_e32 v241, 0xffff0000, v180
	v_add_f32_e32 v244, v244, v240
	v_add_f32_e32 v244, v244, v241
	v_lshlrev_b32_e32 v240, 16, v181
	v_and_b32_e32 v241, 0xffff0000, v181
	v_add_f32_e32 v244, v244, v240
	v_add_f32_e32 v244, v244, v241
	v_lshlrev_b32_e32 v240, 16, v182
	v_and_b32_e32 v241, 0xffff0000, v182
	v_add_f32_e32 v244, v244, v240
	v_add_f32_e32 v244, v244, v241
	v_lshlrev_b32_e32 v240, 16, v183
	v_and_b32_e32 v241, 0xffff0000, v183
	v_add_f32_e32 v244, v244, v240
	v_add_f32_e32 v244, v244, v241
	v_lshlrev_b32_e32 v240, 16, v184
	v_and_b32_e32 v241, 0xffff0000, v184
	v_add_f32_e32 v244, v244, v240
	v_add_f32_e32 v244, v244, v241
	v_lshlrev_b32_e32 v240, 16, v185
	v_and_b32_e32 v241, 0xffff0000, v185
	v_add_f32_e32 v244, v244, v240
	v_add_f32_e32 v244, v244, v241
	v_mov_b32_e32 v240, v244
	s_nop 1
	v_permlane16_swap_b32_e32 v240, v244
	v_add_f32_e32 v244, v244, v240
	v_mov_b32_e32 v240, v244
	s_nop 1
	v_permlane32_swap_b32_e32 v240, v244
	v_add_f32_e32 v244, v244, v240
	v_mul_f32_e32 v238, 0x3c800000, v244
	v_lshlrev_b32_e32 v240, 16, v178
	v_and_b32_e32 v241, 0xffff0000, v178
	v_sub_f32_e32 v240, v240, v238
	v_sub_f32_e32 v241, v241, v238
	v_mul_f32_e32 v245, v240, v240
	v_fmac_f32_e32 v245, v241, v241
	v_lshlrev_b32_e32 v240, 16, v179
	v_and_b32_e32 v241, 0xffff0000, v179
	v_sub_f32_e32 v240, v240, v238
	v_sub_f32_e32 v241, v241, v238
	v_fmac_f32_e32 v245, v240, v240
	v_fmac_f32_e32 v245, v241, v241
	v_lshlrev_b32_e32 v240, 16, v180
	v_and_b32_e32 v241, 0xffff0000, v180
	v_sub_f32_e32 v240, v240, v238
	v_sub_f32_e32 v241, v241, v238
	v_fmac_f32_e32 v245, v240, v240
	v_fmac_f32_e32 v245, v241, v241
	v_lshlrev_b32_e32 v240, 16, v181
	v_and_b32_e32 v241, 0xffff0000, v181
	v_sub_f32_e32 v240, v240, v238
	v_sub_f32_e32 v241, v241, v238
	v_fmac_f32_e32 v245, v240, v240
	v_fmac_f32_e32 v245, v241, v241
	v_lshlrev_b32_e32 v240, 16, v182
	v_and_b32_e32 v241, 0xffff0000, v182
	v_sub_f32_e32 v240, v240, v238
	v_sub_f32_e32 v241, v241, v238
	v_fmac_f32_e32 v245, v240, v240
	v_fmac_f32_e32 v245, v241, v241
	v_lshlrev_b32_e32 v240, 16, v183
	v_and_b32_e32 v241, 0xffff0000, v183
	v_sub_f32_e32 v240, v240, v238
	v_sub_f32_e32 v241, v241, v238
	v_fmac_f32_e32 v245, v240, v240
	v_fmac_f32_e32 v245, v241, v241
	v_lshlrev_b32_e32 v240, 16, v184
	v_and_b32_e32 v241, 0xffff0000, v184
	v_sub_f32_e32 v240, v240, v238
	v_sub_f32_e32 v241, v241, v238
	v_fmac_f32_e32 v245, v240, v240
	v_fmac_f32_e32 v245, v241, v241
	v_lshlrev_b32_e32 v240, 16, v185
	v_and_b32_e32 v241, 0xffff0000, v185
	v_sub_f32_e32 v240, v240, v238
	v_sub_f32_e32 v241, v241, v238
	v_fmac_f32_e32 v245, v240, v240
	v_fmac_f32_e32 v245, v241, v241
	v_mov_b32_e32 v240, v245
	s_nop 1
	v_permlane16_swap_b32_e32 v240, v245
	v_add_f32_e32 v245, v245, v240
	v_mov_b32_e32 v240, v245
	s_nop 1
	v_permlane32_swap_b32_e32 v240, v245
	v_add_f32_e32 v245, v245, v240
	v_mov_b32_e32 v240, 0x3a27c5ac
	v_fmamk_f32 v245, v245, 0x3c800000, v240
	v_rsq_f32_e32 v239, v245
	v_and_b32_e32 v240, 3, v248
	v_cmp_eq_u32_e32 vcc, 0, v240
	s_nop 1
	v_lshlrev_b32_e32 v240, 16, v178
	v_and_b32_e32 v244, 0xffff0000, v178
	v_sub_f32_e32 v240, v240, v238
	v_sub_f32_e32 v244, v244, v238
	v_mul_f32_e32 v240, v240, v239
	v_mul_f32_e32 v244, v244, v239
	v_fma_f32 v240, v130, v240, v146
	v_fma_f32 v244, v131, v244, v147
	v_lshlrev_b32_e32 v241, 16, v186
	v_and_b32_e32 v245, 0xffff0000, v186
	v_lshlrev_b32_e32 v243, 16, v194
	v_and_b32_e32 v246, 0xffff0000, v194
	v_cndmask_b32_e32 v243, v243, v202, vcc
	v_cndmask_b32_e32 v246, v246, v203, vcc
	v_sub_f32_e32 v243, v243, v241
	v_sub_f32_e32 v246, v246, v245
	v_fmac_f32_e32 v241, v162, v243
	v_fmac_f32_e32 v245, v163, v246
	v_fmac_f32_e32 v240, v234, v241
	v_fmac_f32_e32 v244, v234, v245
	v_mul_f32_e32 v16, v16, v240
	v_mul_f32_e32 v17, v17, v244
	v_lshlrev_b32_e32 v240, 16, v179
	v_and_b32_e32 v244, 0xffff0000, v179
	v_sub_f32_e32 v240, v240, v238
	v_sub_f32_e32 v244, v244, v238
	v_mul_f32_e32 v240, v240, v239
	v_mul_f32_e32 v244, v244, v239
	v_fma_f32 v240, v132, v240, v148
	v_fma_f32 v244, v133, v244, v149
	v_lshlrev_b32_e32 v241, 16, v187
	v_and_b32_e32 v245, 0xffff0000, v187
	v_lshlrev_b32_e32 v243, 16, v195
	v_and_b32_e32 v246, 0xffff0000, v195
	v_cndmask_b32_e32 v243, v243, v204, vcc
	v_cndmask_b32_e32 v246, v246, v205, vcc
	v_sub_f32_e32 v243, v243, v241
	v_sub_f32_e32 v246, v246, v245
	v_fmac_f32_e32 v241, v164, v243
	v_fmac_f32_e32 v245, v165, v246
	v_fmac_f32_e32 v240, v234, v241
	v_fmac_f32_e32 v244, v234, v245
	v_mul_f32_e32 v18, v18, v240
	v_mul_f32_e32 v19, v19, v244
	v_lshlrev_b32_e32 v240, 16, v180
	v_and_b32_e32 v244, 0xffff0000, v180
	v_sub_f32_e32 v240, v240, v238
	v_sub_f32_e32 v244, v244, v238
	v_mul_f32_e32 v240, v240, v239
	v_mul_f32_e32 v244, v244, v239
	v_fma_f32 v240, v134, v240, v150
	v_fma_f32 v244, v135, v244, v151
	v_lshlrev_b32_e32 v241, 16, v188
	v_and_b32_e32 v245, 0xffff0000, v188
	v_lshlrev_b32_e32 v243, 16, v196
	v_and_b32_e32 v246, 0xffff0000, v196
	v_cndmask_b32_e32 v243, v243, v206, vcc
	v_cndmask_b32_e32 v246, v246, v207, vcc
	v_sub_f32_e32 v243, v243, v241
	v_sub_f32_e32 v246, v246, v245
	v_fmac_f32_e32 v241, v166, v243
	v_fmac_f32_e32 v245, v167, v246
	v_fmac_f32_e32 v240, v234, v241
	v_fmac_f32_e32 v244, v234, v245
	v_mul_f32_e32 v20, v20, v240
	v_mul_f32_e32 v21, v21, v244
	v_lshlrev_b32_e32 v240, 16, v181
	v_and_b32_e32 v244, 0xffff0000, v181
	v_sub_f32_e32 v240, v240, v238
; __device__ __forceinline__ float bf2f(u16 h) { return __uint_as_float(((unsigned)h) << 16); }
; template <int EPI> ...
;     ...
;         float pv0 = bf2f(P[(size_t)row * 2816 + 256 + 1536 + ch0]);
;         float pv1 = bf2f(P[(size_t)row * 2816 + 256 + 1536 + ch1]);
;         float pp0 = prevP(p, P, row, 1536 + ch0), pp1 = prevP(p, P, row, 1536 + ch1);
;         float vv0 = pv0 + (pp0 - pv0) * mu0, vv1 = pv1 + (pp1 - pv1) * mu1;
;         float b = bs[((size_t)row * 12 + hh) * 4 + 2];
;         float y0 = (d0 * rstd * gg0 + gb0 + b * vv0) * acc0[i];
;         float y1 = (d1 * rstd * gg1 + gb1 + b * vv1) * acc1[i];
;         Y[(size_t)row * 1024 + 256 + ch0] = f2bf(y0);
;         Y[(size_t)row * 1024 + 256 + ch1] = f2bf(y1);
;       }
	v_sub_f32_e32 v244, v244, v238
	v_mul_f32_e32 v240, v240, v239
	v_mul_f32_e32 v244, v244, v239
	v_fma_f32 v240, v136, v240, v152
	v_fma_f32 v244, v137, v244, v153
	v_lshlrev_b32_e32 v241, 16, v189
	v_and_b32_e32 v245, 0xffff0000, v189
	v_lshlrev_b32_e32 v243, 16, v197
	v_and_b32_e32 v246, 0xffff0000, v197
	v_cndmask_b32_e32 v243, v243, v208, vcc
	v_cndmask_b32_e32 v246, v246, v209, vcc
	v_sub_f32_e32 v243, v243, v241
	v_sub_f32_e32 v246, v246, v245
	v_fmac_f32_e32 v241, v168, v243
	v_fmac_f32_e32 v245, v169, v246
	v_fmac_f32_e32 v240, v234, v241
	v_fmac_f32_e32 v244, v234, v245
	v_mul_f32_e32 v22, v22, v240
	v_mul_f32_e32 v23, v23, v244
	v_cvt_pk_bf16_f32 v16, v16, v17
	v_cvt_pk_bf16_f32 v17, v18, v19
	v_cvt_pk_bf16_f32 v18, v20, v21
	v_cvt_pk_bf16_f32 v19, v22, v23
	v_add_u32_e32 v236, 0x0, v230
	s_nop 0
	global_store_dwordx4 v236, v[16:19], s[22:23] offset:128
	v_lshlrev_b32_e32 v240, 16, v182
	v_and_b32_e32 v244, 0xffff0000, v182
	v_sub_f32_e32 v240, v240, v238
	v_sub_f32_e32 v244, v244, v238
	v_mul_f32_e32 v240, v240, v239
	v_mul_f32_e32 v244, v244, v239
	v_fma_f32 v240, v138, v240, v154
	v_fma_f32 v244, v139, v244, v155
	v_lshlrev_b32_e32 v241, 16, v190
	v_and_b32_e32 v245, 0xffff0000, v190
	v_lshlrev_b32_e32 v243, 16, v198
	v_and_b32_e32 v246, 0xffff0000, v198
	v_cndmask_b32_e32 v243, v243, v210, vcc
	v_cndmask_b32_e32 v246, v246, v211, vcc
	v_sub_f32_e32 v243, v243, v241
	v_sub_f32_e32 v246, v246, v245
	v_fmac_f32_e32 v241, v170, v243
	v_fmac_f32_e32 v245, v171, v246
	v_fmac_f32_e32 v240, v234, v241
	v_fmac_f32_e32 v244, v234, v245
	v_mul_f32_e32 v24, v24, v240
	v_mul_f32_e32 v25, v25, v244
	v_lshlrev_b32_e32 v240, 16, v183
	v_and_b32_e32 v244, 0xffff0000, v183
	v_sub_f32_e32 v240, v240, v238
	v_sub_f32_e32 v244, v244, v238
	v_mul_f32_e32 v240, v240, v239
	v_mul_f32_e32 v244, v244, v239
	v_fma_f32 v240, v140, v240, v156
	v_fma_f32 v244, v141, v244, v157
	v_lshlrev_b32_e32 v241, 16, v191
	v_and_b32_e32 v245, 0xffff0000, v191
	v_lshlrev_b32_e32 v243, 16, v199
	v_and_b32_e32 v246, 0xffff0000, v199
	v_cndmask_b32_e32 v243, v243, v212, vcc
	v_cndmask_b32_e32 v246, v246, v213, vcc
	v_sub_f32_e32 v243, v243, v241
	v_sub_f32_e32 v246, v246, v245
	v_fmac_f32_e32 v241, v172, v243
	v_fmac_f32_e32 v245, v173, v246
	v_fmac_f32_e32 v240, v234, v241
	v_fmac_f32_e32 v244, v234, v245
	v_mul_f32_e32 v26, v26, v240
	v_mul_f32_e32 v27, v27, v244
	v_lshlrev_b32_e32 v240, 16, v184
	v_and_b32_e32 v244, 0xffff0000, v184
	v_sub_f32_e32 v240, v240, v238
	v_sub_f32_e32 v244, v244, v238
	v_mul_f32_e32 v240, v240, v239
	v_mul_f32_e32 v244, v244, v239
	v_fma_f32 v240, v142, v240, v158
	v_fma_f32 v244, v143, v244, v159
	v_lshlrev_b32_e32 v241, 16, v192
	v_and_b32_e32 v245, 0xffff0000, v192
	v_lshlrev_b32_e32 v243, 16, v200
	v_and_b32_e32 v246, 0xffff0000, v200
	v_cndmask_b32_e32 v243, v243, v214, vcc
	v_cndmask_b32_e32 v246, v246, v215, vcc
	v_sub_f32_e32 v243, v243, v241
	v_sub_f32_e32 v246, v246, v245
	v_fmac_f32_e32 v241, v174, v243
	v_fmac_f32_e32 v245, v175, v246
	v_fmac_f32_e32 v240, v234, v241
	v_fmac_f32_e32 v244, v234, v245
	v_mul_f32_e32 v28, v28, v240
	v_mul_f32_e32 v29, v29, v244
	v_lshlrev_b32_e32 v240, 16, v185
	v_and_b32_e32 v244, 0xffff0000, v185
	v_sub_f32_e32 v240, v240, v238
	v_sub_f32_e32 v244, v244, v238
	v_mul_f32_e32 v240, v240, v239
	v_mul_f32_e32 v244, v244, v239
	v_fma_f32 v240, v144, v240, v160
	v_fma_f32 v244, v145, v244, v161
	v_lshlrev_b32_e32 v241, 16, v193
	v_and_b32_e32 v245, 0xffff0000, v193
	v_lshlrev_b32_e32 v243, 16, v201
	v_and_b32_e32 v246, 0xffff0000, v201
	v_cndmask_b32_e32 v243, v243, v216, vcc
	v_cndmask_b32_e32 v246, v246, v217, vcc
	v_sub_f32_e32 v243, v243, v241
	v_sub_f32_e32 v246, v246, v245
	v_fmac_f32_e32 v241, v176, v243
	v_fmac_f32_e32 v245, v177, v246
	v_fmac_f32_e32 v240, v234, v241
	v_fmac_f32_e32 v244, v234, v245
	v_mul_f32_e32 v30, v30, v240
	v_mul_f32_e32 v31, v31, v244
	v_cvt_pk_bf16_f32 v24, v24, v25
	v_cvt_pk_bf16_f32 v25, v26, v27
	v_cvt_pk_bf16_f32 v26, v28, v29
	v_cvt_pk_bf16_f32 v27, v30, v31
	v_add_u32_e32 v236, 0x0, v230
	s_nop 0
	global_store_dwordx4 v236, v[24:27], s[22:23] offset:192
	v_add_u32_e32 v236, 0x8000, v230
	v_add_u32_e32 v237, 0x16000, v231
	v_subrev_u32_e32 v240, 0x1600, v237
	global_load_dwordx4 v[178:181], v236, s[22:23] offset:128
	global_load_dwordx4 v[182:185], v236, s[22:23] offset:192
	global_load_dwordx4 v[186:189], v237, s[96:97] offset:128
	global_load_dwordx4 v[190:193], v237, s[96:97] offset:192
	global_load_dwordx4 v[194:197], v240, s[96:97] offset:128
	global_load_dwordx4 v[198:201], v240, s[96:97] offset:192
	v_add_u32_e32 v236, 0xc00, v232
	s_nop 0
	global_load_dword v234, v236, s[96:97] offset:16
	v_add_u32_e32 v237, 0xa000, v247
	global_load_dwordx4 v[202:205], v237, s[20:21] offset:256
	global_load_dwordx4 v[206:209], v237, s[20:21] offset:272
	global_load_dwordx4 v[210:213], v237, s[20:21] offset:384
	global_load_dwordx4 v[214:217], v237, s[20:21] offset:400
	s_waitcnt vmcnt(0)
; __device__ __forceinline__ float bf2f(u16 h) { return __uint_as_float(((unsigned)h) << 16); }
; __device__ __forceinline__ float prevP(const Params& p, const u16* P, int row, int c) {
;   const int rp = row > 0 ? row - 1 : 0;
;   float v = bf2f(P[(size_t)rp * 2816 + 256 + c]);
;   const bool start = (row < NP) ? ((row & 2047) == 0) : (((row - NP) & 3) == 0);
;   if (start) v = (row < NP) ? 0.f : p.in[3][(size_t)((row - NP) >> 2) * 2560 + c];
; template <int EPI> ...
;     ...
;       for (int i = 0; i < 16; i++) {
;         const int rl = rbase + (i & 3) + 8 * (i >> 2);
;         const int row = m0 + rl;
;         float o0 = bf2f(Y[(size_t)row * 1024 + 256 + ch0]);
;         float o1 = bf2f(Y[(size_t)row * 1024 + 256 + ch1]);
;         float mean = hsum32(o0 + o1) * (1.0f / 64.0f);
;         float d0 = o0 - mean, d1 = o1 - mean;
;         float var = hsum32(d0 * d0 + d1 * d1) * (1.0f / 64.0f);
;         float rstd = rsqrtf(var + 64e-5f);
;         float pv0 = bf2f(P[(size_t)row * 2816 + 256 + 1536 + ch0]);
;         float pv1 = bf2f(P[(size_t)row * 2816 + 256 + 1536 + ch1]);
;         float pp0 = prevP(p, P, row, 1536 + ch0), pp1 = prevP(p, P, row, 1536 + ch1);
;         float vv0 = pv0 + (pp0 - pv0) * mu0, vv1 = pv1 + (pp1 - pv1) * mu1;
;         float b = bs[((size_t)row * 12 + hh) * 4 + 2];
;         float y0 = (d0 * rstd * gg0 + gb0 + b * vv0) * acc0[i];
;         float y1 = (d1 * rstd * gg1 + gb1 + b * vv1) * acc1[i];
	v_lshlrev_b32_e32 v240, 16, v178
	v_and_b32_e32 v241, 0xffff0000, v178
	v_add_f32_e32 v244, v240, v241
	v_lshlrev_b32_e32 v240, 16, v179
	v_and_b32_e32 v241, 0xffff0000, v179
	v_add_f32_e32 v244, v244, v240
	v_add_f32_e32 v244, v244, v241
	v_lshlrev_b32_e32 v240, 16, v180
	v_and_b32_e32 v241, 0xffff0000, v180
	v_add_f32_e32 v244, v244, v240
	v_add_f32_e32 v244, v244, v241
	v_lshlrev_b32_e32 v240, 16, v181
	v_and_b32_e32 v241, 0xffff0000, v181
	v_add_f32_e32 v244, v244, v240
	v_add_f32_e32 v244, v244, v241
	v_lshlrev_b32_e32 v240, 16, v182
	v_and_b32_e32 v241, 0xffff0000, v182
	v_add_f32_e32 v244, v244, v240
	v_add_f32_e32 v244, v244, v241
	v_lshlrev_b32_e32 v240, 16, v183
	v_and_b32_e32 v241, 0xffff0000, v183
	v_add_f32_e32 v244, v244, v240
	v_add_f32_e32 v244, v244, v241
	v_lshlrev_b32_e32 v240, 16, v184
	v_and_b32_e32 v241, 0xffff0000, v184
	v_add_f32_e32 v244, v244, v240
	v_add_f32_e32 v244, v244, v241
	v_lshlrev_b32_e32 v240, 16, v185
	v_and_b32_e32 v241, 0xffff0000, v185
	v_add_f32_e32 v244, v244, v240
	v_add_f32_e32 v244, v244, v241
	v_mov_b32_e32 v240, v244
	s_nop 1
	v_permlane16_swap_b32_e32 v240, v244
	v_add_f32_e32 v244, v244, v240
	v_mov_b32_e32 v240, v244
	s_nop 1
	v_permlane32_swap_b32_e32 v240, v244
	v_add_f32_e32 v244, v244, v240
	v_mul_f32_e32 v238, 0x3c800000, v244
	v_lshlrev_b32_e32 v240, 16, v178
	v_and_b32_e32 v241, 0xffff0000, v178
	v_sub_f32_e32 v240, v240, v238
	v_sub_f32_e32 v241, v241, v238
	v_mul_f32_e32 v245, v240, v240
	v_fmac_f32_e32 v245, v241, v241
	v_lshlrev_b32_e32 v240, 16, v179
	v_and_b32_e32 v241, 0xffff0000, v179
	v_sub_f32_e32 v240, v240, v238
	v_sub_f32_e32 v241, v241, v238
	v_fmac_f32_e32 v245, v240, v240
	v_fmac_f32_e32 v245, v241, v241
	v_lshlrev_b32_e32 v240, 16, v180
	v_and_b32_e32 v241, 0xffff0000, v180
	v_sub_f32_e32 v240, v240, v238
	v_sub_f32_e32 v241, v241, v238
	v_fmac_f32_e32 v245, v240, v240
	v_fmac_f32_e32 v245, v241, v241
	v_lshlrev_b32_e32 v240, 16, v181
	v_and_b32_e32 v241, 0xffff0000, v181
	v_sub_f32_e32 v240, v240, v238
	v_sub_f32_e32 v241, v241, v238
	v_fmac_f32_e32 v245, v240, v240
	v_fmac_f32_e32 v245, v241, v241
	v_lshlrev_b32_e32 v240, 16, v182
	v_and_b32_e32 v241, 0xffff0000, v182
	v_sub_f32_e32 v240, v240, v238
	v_sub_f32_e32 v241, v241, v238
	v_fmac_f32_e32 v245, v240, v240
	v_fmac_f32_e32 v245, v241, v241
	v_lshlrev_b32_e32 v240, 16, v183
	v_and_b32_e32 v241, 0xffff0000, v183
	v_sub_f32_e32 v240, v240, v238
	v_sub_f32_e32 v241, v241, v238
	v_fmac_f32_e32 v245, v240, v240
	v_fmac_f32_e32 v245, v241, v241
	v_lshlrev_b32_e32 v240, 16, v184
	v_and_b32_e32 v241, 0xffff0000, v184
	v_sub_f32_e32 v240, v240, v238
	v_sub_f32_e32 v241, v241, v238
	v_fmac_f32_e32 v245, v240, v240
	v_fmac_f32_e32 v245, v241, v241
	v_lshlrev_b32_e32 v240, 16, v185
	v_and_b32_e32 v241, 0xffff0000, v185
	v_sub_f32_e32 v240, v240, v238
	v_sub_f32_e32 v241, v241, v238
	v_fmac_f32_e32 v245, v240, v240
	v_fmac_f32_e32 v245, v241, v241
	v_mov_b32_e32 v240, v245
	s_nop 1
	v_permlane16_swap_b32_e32 v240, v245
	v_add_f32_e32 v245, v245, v240
	v_mov_b32_e32 v240, v245
	s_nop 1
	v_permlane32_swap_b32_e32 v240, v245
	v_add_f32_e32 v245, v245, v240
	v_mov_b32_e32 v240, 0x3a27c5ac
	v_fmamk_f32 v245, v245, 0x3c800000, v240
	v_rsq_f32_e32 v239, v245
	v_and_b32_e32 v240, 3, v248
	v_cmp_eq_u32_e32 vcc, 0, v240
	s_nop 1
	v_lshlrev_b32_e32 v240, 16, v178
	v_and_b32_e32 v244, 0xffff0000, v178
	v_sub_f32_e32 v240, v240, v238
	v_sub_f32_e32 v244, v244, v238
	v_mul_f32_e32 v240, v240, v239
	v_mul_f32_e32 v244, v244, v239
	v_fma_f32 v240, v130, v240, v146
	v_fma_f32 v244, v131, v244, v147
	v_lshlrev_b32_e32 v241, 16, v186
	v_and_b32_e32 v245, 0xffff0000, v186
	v_lshlrev_b32_e32 v243, 16, v194
	v_and_b32_e32 v246, 0xffff0000, v194
	v_cndmask_b32_e32 v243, v243, v202, vcc
	v_cndmask_b32_e32 v246, v246, v203, vcc
	v_sub_f32_e32 v243, v243, v241
	v_sub_f32_e32 v246, v246, v245
	v_fmac_f32_e32 v241, v162, v243
	v_fmac_f32_e32 v245, v163, v246
	v_fmac_f32_e32 v240, v234, v241
	v_fmac_f32_e32 v244, v234, v245
	v_mul_f32_e32 v48, v48, v240
	v_mul_f32_e32 v49, v49, v244
	v_lshlrev_b32_e32 v240, 16, v179
	v_and_b32_e32 v244, 0xffff0000, v179
	v_sub_f32_e32 v240, v240, v238
	v_sub_f32_e32 v244, v244, v238
	v_mul_f32_e32 v240, v240, v239
	v_mul_f32_e32 v244, v244, v239
	v_fma_f32 v240, v132, v240, v148
	v_fma_f32 v244, v133, v244, v149
	v_lshlrev_b32_e32 v241, 16, v187
	v_and_b32_e32 v245, 0xffff0000, v187
	v_lshlrev_b32_e32 v243, 16, v195
	v_and_b32_e32 v246, 0xffff0000, v195
	v_cndmask_b32_e32 v243, v243, v204, vcc
	v_cndmask_b32_e32 v246, v246, v205, vcc
	v_sub_f32_e32 v243, v243, v241
	v_sub_f32_e32 v246, v246, v245
	v_fmac_f32_e32 v241, v164, v243
	v_fmac_f32_e32 v245, v165, v246
	v_fmac_f32_e32 v240, v234, v241
	v_fmac_f32_e32 v244, v234, v245
	v_mul_f32_e32 v50, v50, v240
	v_mul_f32_e32 v51, v51, v244
	v_lshlrev_b32_e32 v240, 16, v180
	v_and_b32_e32 v244, 0xffff0000, v180
	v_sub_f32_e32 v240, v240, v238
	v_sub_f32_e32 v244, v244, v238
	v_mul_f32_e32 v240, v240, v239
	v_mul_f32_e32 v244, v244, v239
	v_fma_f32 v240, v134, v240, v150
	v_fma_f32 v244, v135, v244, v151
	v_lshlrev_b32_e32 v241, 16, v188
	v_and_b32_e32 v245, 0xffff0000, v188
	v_lshlrev_b32_e32 v243, 16, v196
	v_and_b32_e32 v246, 0xffff0000, v196
	v_cndmask_b32_e32 v243, v243, v206, vcc
	v_cndmask_b32_e32 v246, v246, v207, vcc
	v_sub_f32_e32 v243, v243, v241
	v_sub_f32_e32 v246, v246, v245
	v_fmac_f32_e32 v241, v166, v243
	v_fmac_f32_e32 v245, v167, v246
	v_fmac_f32_e32 v240, v234, v241
	v_fmac_f32_e32 v244, v234, v245
	v_mul_f32_e32 v52, v52, v240
	v_mul_f32_e32 v53, v53, v244
	v_lshlrev_b32_e32 v240, 16, v181
	v_and_b32_e32 v244, 0xffff0000, v181
	v_sub_f32_e32 v240, v240, v238
; __device__ __forceinline__ float bf2f(u16 h) { return __uint_as_float(((unsigned)h) << 16); }
; template <int EPI> ...
;     ...
;         float d0 = o0 - mean, d1 = o1 - mean;
;         float var = hsum32(d0 * d0 + d1 * d1) * (1.0f / 64.0f);
;         float rstd = rsqrtf(var + 64e-5f);
;         float pv0 = bf2f(P[(size_t)row * 2816 + 256 + 1536 + ch0]);
;         float pv1 = bf2f(P[(size_t)row * 2816 + 256 + 1536 + ch1]);
;         float pp0 = prevP(p, P, row, 1536 + ch0), pp1 = prevP(p, P, row, 1536 + ch1);
;         float vv0 = pv0 + (pp0 - pv0) * mu0, vv1 = pv1 + (pp1 - pv1) * mu1;
;         float b = bs[((size_t)row * 12 + hh) * 4 + 2];
;         float y0 = (d0 * rstd * gg0 + gb0 + b * vv0) * acc0[i];
;         float y1 = (d1 * rstd * gg1 + gb1 + b * vv1) * acc1[i];
;         Y[(size_t)row * 1024 + 256 + ch0] = f2bf(y0);
;         Y[(size_t)row * 1024 + 256 + ch1] = f2bf(y1);
;       }
	v_sub_f32_e32 v244, v244, v238
	v_mul_f32_e32 v240, v240, v239
	v_mul_f32_e32 v244, v244, v239
	v_fma_f32 v240, v136, v240, v152
	v_fma_f32 v244, v137, v244, v153
	v_lshlrev_b32_e32 v241, 16, v189
	v_and_b32_e32 v245, 0xffff0000, v189
	v_lshlrev_b32_e32 v243, 16, v197
	v_and_b32_e32 v246, 0xffff0000, v197
	v_cndmask_b32_e32 v243, v243, v208, vcc
	v_cndmask_b32_e32 v246, v246, v209, vcc
	v_sub_f32_e32 v243, v243, v241
	v_sub_f32_e32 v246, v246, v245
	v_fmac_f32_e32 v241, v168, v243
	v_fmac_f32_e32 v245, v169, v246
	v_fmac_f32_e32 v240, v234, v241
	v_fmac_f32_e32 v244, v234, v245
	v_mul_f32_e32 v54, v54, v240
	v_mul_f32_e32 v55, v55, v244
	v_cvt_pk_bf16_f32 v48, v48, v49
	v_cvt_pk_bf16_f32 v49, v50, v51
	v_cvt_pk_bf16_f32 v50, v52, v53
	v_cvt_pk_bf16_f32 v51, v54, v55
	v_add_u32_e32 v236, 0x8000, v230
	s_nop 0
	global_store_dwordx4 v236, v[48:51], s[22:23] offset:128
	v_lshlrev_b32_e32 v240, 16, v182
	v_and_b32_e32 v244, 0xffff0000, v182
	v_sub_f32_e32 v240, v240, v238
	v_sub_f32_e32 v244, v244, v238
	v_mul_f32_e32 v240, v240, v239
	v_mul_f32_e32 v244, v244, v239
	v_fma_f32 v240, v138, v240, v154
	v_fma_f32 v244, v139, v244, v155
	v_lshlrev_b32_e32 v241, 16, v190
	v_and_b32_e32 v245, 0xffff0000, v190
	v_lshlrev_b32_e32 v243, 16, v198
	v_and_b32_e32 v246, 0xffff0000, v198
	v_cndmask_b32_e32 v243, v243, v210, vcc
	v_cndmask_b32_e32 v246, v246, v211, vcc
	v_sub_f32_e32 v243, v243, v241
	v_sub_f32_e32 v246, v246, v245
	v_fmac_f32_e32 v241, v170, v243
	v_fmac_f32_e32 v245, v171, v246
	v_fmac_f32_e32 v240, v234, v241
	v_fmac_f32_e32 v244, v234, v245
	v_mul_f32_e32 v56, v56, v240
	v_mul_f32_e32 v57, v57, v244
	v_lshlrev_b32_e32 v240, 16, v183
	v_and_b32_e32 v244, 0xffff0000, v183
	v_sub_f32_e32 v240, v240, v238
	v_sub_f32_e32 v244, v244, v238
	v_mul_f32_e32 v240, v240, v239
	v_mul_f32_e32 v244, v244, v239
	v_fma_f32 v240, v140, v240, v156
	v_fma_f32 v244, v141, v244, v157
	v_lshlrev_b32_e32 v241, 16, v191
	v_and_b32_e32 v245, 0xffff0000, v191
	v_lshlrev_b32_e32 v243, 16, v199
	v_and_b32_e32 v246, 0xffff0000, v199
	v_cndmask_b32_e32 v243, v243, v212, vcc
	v_cndmask_b32_e32 v246, v246, v213, vcc
	v_sub_f32_e32 v243, v243, v241
	v_sub_f32_e32 v246, v246, v245
	v_fmac_f32_e32 v241, v172, v243
	v_fmac_f32_e32 v245, v173, v246
	v_fmac_f32_e32 v240, v234, v241
	v_fmac_f32_e32 v244, v234, v245
	v_mul_f32_e32 v58, v58, v240
	v_mul_f32_e32 v59, v59, v244
	v_lshlrev_b32_e32 v240, 16, v184
	v_and_b32_e32 v244, 0xffff0000, v184
	v_sub_f32_e32 v240, v240, v238
	v_sub_f32_e32 v244, v244, v238
	v_mul_f32_e32 v240, v240, v239
	v_mul_f32_e32 v244, v244, v239
	v_fma_f32 v240, v142, v240, v158
	v_fma_f32 v244, v143, v244, v159
	v_lshlrev_b32_e32 v241, 16, v192
	v_and_b32_e32 v245, 0xffff0000, v192
	v_lshlrev_b32_e32 v243, 16, v200
	v_and_b32_e32 v246, 0xffff0000, v200
	v_cndmask_b32_e32 v243, v243, v214, vcc
	v_cndmask_b32_e32 v246, v246, v215, vcc
	v_sub_f32_e32 v243, v243, v241
	v_sub_f32_e32 v246, v246, v245
	v_fmac_f32_e32 v241, v174, v243
	v_fmac_f32_e32 v245, v175, v246
	v_fmac_f32_e32 v240, v234, v241
	v_fmac_f32_e32 v244, v234, v245
	v_mul_f32_e32 v60, v60, v240
	v_mul_f32_e32 v61, v61, v244
	v_lshlrev_b32_e32 v240, 16, v185
	v_and_b32_e32 v244, 0xffff0000, v185
	v_sub_f32_e32 v240, v240, v238
	v_sub_f32_e32 v244, v244, v238
	v_mul_f32_e32 v240, v240, v239
	v_mul_f32_e32 v244, v244, v239
	v_fma_f32 v240, v144, v240, v160
	v_fma_f32 v244, v145, v244, v161
	v_lshlrev_b32_e32 v241, 16, v193
	v_and_b32_e32 v245, 0xffff0000, v193
	v_lshlrev_b32_e32 v243, 16, v201
	v_and_b32_e32 v246, 0xffff0000, v201
	v_cndmask_b32_e32 v243, v243, v216, vcc
	v_cndmask_b32_e32 v246, v246, v217, vcc
	v_sub_f32_e32 v243, v243, v241
	v_sub_f32_e32 v246, v246, v245
	v_fmac_f32_e32 v241, v176, v243
	v_fmac_f32_e32 v245, v177, v246
	v_fmac_f32_e32 v240, v234, v241
	v_fmac_f32_e32 v244, v234, v245
	v_mul_f32_e32 v62, v62, v240
	v_mul_f32_e32 v63, v63, v244
	v_cvt_pk_bf16_f32 v56, v56, v57
	v_cvt_pk_bf16_f32 v57, v58, v59
	v_cvt_pk_bf16_f32 v58, v60, v61
	v_cvt_pk_bf16_f32 v59, v62, v63
	v_add_u32_e32 v236, 0x8000, v230
	s_nop 0
	global_store_dwordx4 v236, v[56:59], s[22:23] offset:192
	v_add_u32_e32 v236, 0x10000, v230
	v_add_u32_e32 v237, 0x2c000, v231
	v_subrev_u32_e32 v240, 0x1600, v237
	global_load_dwordx4 v[178:181], v236, s[22:23] offset:128
	global_load_dwordx4 v[182:185], v236, s[22:23] offset:192
	global_load_dwordx4 v[186:189], v237, s[96:97] offset:128
	global_load_dwordx4 v[190:193], v237, s[96:97] offset:192
	global_load_dwordx4 v[194:197], v240, s[96:97] offset:128
	global_load_dwordx4 v[198:201], v240, s[96:97] offset:192
	v_add_u32_e32 v236, 0x1800, v232
	s_nop 0
	global_load_dword v234, v236, s[96:97] offset:16
	v_add_u32_e32 v237, 0x14000, v247
	global_load_dwordx4 v[202:205], v237, s[20:21] offset:256
	global_load_dwordx4 v[206:209], v237, s[20:21] offset:272
	global_load_dwordx4 v[210:213], v237, s[20:21] offset:384
	global_load_dwordx4 v[214:217], v237, s[20:21] offset:400
	s_waitcnt vmcnt(0)
; __device__ __forceinline__ float bf2f(u16 h) { return __uint_as_float(((unsigned)h) << 16); }
; template <int EPI> ...
;     ...
;       for (int i = 0; i < 16; i++) {
;         const int rl = rbase + (i & 3) + 8 * (i >> 2);
;         const int row = m0 + rl;
;         float o0 = bf2f(Y[(size_t)row * 1024 + 256 + ch0]);
;         float o1 = bf2f(Y[(size_t)row * 1024 + 256 + ch1]);
;         float mean = hsum32(o0 + o1) * (1.0f / 64.0f);
;         float d0 = o0 - mean, d1 = o1 - mean;
;         float var = hsum32(d0 * d0 + d1 * d1) * (1.0f / 64.0f);
;         float rstd = rsqrtf(var + 64e-5f);
;         float pv0 = bf2f(P[(size_t)row * 2816 + 256 + 1536 + ch0]);
;         float pv1 = bf2f(P[(size_t)row * 2816 + 256 + 1536 + ch1]);
;         float pp0 = prevP(p, P, row, 1536 + ch0), pp1 = prevP(p, P, row, 1536 + ch1);
;         float vv0 = pv0 + (pp0 - pv0) * mu0, vv1 = pv1 + (pp1 - pv1) * mu1;
;         float b = bs[((size_t)row * 12 + hh) * 4 + 2];
;         float y0 = (d0 * rstd * gg0 + gb0 + b * vv0) * acc0[i];
;         float y1 = (d1 * rstd * gg1 + gb1 + b * vv1) * acc1[i];
	v_lshlrev_b32_e32 v240, 16, v178
	v_and_b32_e32 v241, 0xffff0000, v178
	v_add_f32_e32 v244, v240, v241
	v_lshlrev_b32_e32 v240, 16, v179
	v_and_b32_e32 v241, 0xffff0000, v179
	v_add_f32_e32 v244, v244, v240
	v_add_f32_e32 v244, v244, v241
	v_lshlrev_b32_e32 v240, 16, v180
	v_and_b32_e32 v241, 0xffff0000, v180
	v_add_f32_e32 v244, v244, v240
	v_add_f32_e32 v244, v244, v241
	v_lshlrev_b32_e32 v240, 16, v181
	v_and_b32_e32 v241, 0xffff0000, v181
	v_add_f32_e32 v244, v244, v240
	v_add_f32_e32 v244, v244, v241
	v_lshlrev_b32_e32 v240, 16, v182
	v_and_b32_e32 v241, 0xffff0000, v182
	v_add_f32_e32 v244, v244, v240
	v_add_f32_e32 v244, v244, v241
	v_lshlrev_b32_e32 v240, 16, v183
	v_and_b32_e32 v241, 0xffff0000, v183
	v_add_f32_e32 v244, v244, v240
	v_add_f32_e32 v244, v244, v241
	v_lshlrev_b32_e32 v240, 16, v184
	v_and_b32_e32 v241, 0xffff0000, v184
	v_add_f32_e32 v244, v244, v240
	v_add_f32_e32 v244, v244, v241
	v_lshlrev_b32_e32 v240, 16, v185
	v_and_b32_e32 v241, 0xffff0000, v185
	v_add_f32_e32 v244, v244, v240
	v_add_f32_e32 v244, v244, v241
	v_mov_b32_e32 v240, v244
	s_nop 1
	v_permlane16_swap_b32_e32 v240, v244
	v_add_f32_e32 v244, v244, v240
	v_mov_b32_e32 v240, v244
	s_nop 1
	v_permlane32_swap_b32_e32 v240, v244
	v_add_f32_e32 v244, v244, v240
	v_mul_f32_e32 v238, 0x3c800000, v244
	v_lshlrev_b32_e32 v240, 16, v178
	v_and_b32_e32 v241, 0xffff0000, v178
	v_sub_f32_e32 v240, v240, v238
	v_sub_f32_e32 v241, v241, v238
	v_mul_f32_e32 v245, v240, v240
	v_fmac_f32_e32 v245, v241, v241
	v_lshlrev_b32_e32 v240, 16, v179
	v_and_b32_e32 v241, 0xffff0000, v179
	v_sub_f32_e32 v240, v240, v238
	v_sub_f32_e32 v241, v241, v238
	v_fmac_f32_e32 v245, v240, v240
	v_fmac_f32_e32 v245, v241, v241
	v_lshlrev_b32_e32 v240, 16, v180
	v_and_b32_e32 v241, 0xffff0000, v180
	v_sub_f32_e32 v240, v240, v238
	v_sub_f32_e32 v241, v241, v238
	v_fmac_f32_e32 v245, v240, v240
	v_fmac_f32_e32 v245, v241, v241
	v_lshlrev_b32_e32 v240, 16, v181
	v_and_b32_e32 v241, 0xffff0000, v181
	v_sub_f32_e32 v240, v240, v238
	v_sub_f32_e32 v241, v241, v238
	v_fmac_f32_e32 v245, v240, v240
	v_fmac_f32_e32 v245, v241, v241
	v_lshlrev_b32_e32 v240, 16, v182
	v_and_b32_e32 v241, 0xffff0000, v182
	v_sub_f32_e32 v240, v240, v238
	v_sub_f32_e32 v241, v241, v238
	v_fmac_f32_e32 v245, v240, v240
	v_fmac_f32_e32 v245, v241, v241
	v_lshlrev_b32_e32 v240, 16, v183
	v_and_b32_e32 v241, 0xffff0000, v183
	v_sub_f32_e32 v240, v240, v238
	v_sub_f32_e32 v241, v241, v238
	v_fmac_f32_e32 v245, v240, v240
	v_fmac_f32_e32 v245, v241, v241
	v_lshlrev_b32_e32 v240, 16, v184
	v_and_b32_e32 v241, 0xffff0000, v184
	v_sub_f32_e32 v240, v240, v238
	v_sub_f32_e32 v241, v241, v238
	v_fmac_f32_e32 v245, v240, v240
	v_fmac_f32_e32 v245, v241, v241
	v_lshlrev_b32_e32 v240, 16, v185
	v_and_b32_e32 v241, 0xffff0000, v185
	v_sub_f32_e32 v240, v240, v238
	v_sub_f32_e32 v241, v241, v238
	v_fmac_f32_e32 v245, v240, v240
	v_fmac_f32_e32 v245, v241, v241
	v_mov_b32_e32 v240, v245
	s_nop 1
	v_permlane16_swap_b32_e32 v240, v245
	v_add_f32_e32 v245, v245, v240
	v_mov_b32_e32 v240, v245
	s_nop 1
	v_permlane32_swap_b32_e32 v240, v245
	v_add_f32_e32 v245, v245, v240
	v_mov_b32_e32 v240, 0x3a27c5ac
	v_fmamk_f32 v245, v245, 0x3c800000, v240
	v_rsq_f32_e32 v239, v245
	v_and_b32_e32 v240, 3, v248
	v_cmp_eq_u32_e32 vcc, 0, v240
	s_nop 1
	v_lshlrev_b32_e32 v240, 16, v178
	v_and_b32_e32 v244, 0xffff0000, v178
	v_sub_f32_e32 v240, v240, v238
	v_sub_f32_e32 v244, v244, v238
	v_mul_f32_e32 v240, v240, v239
	v_mul_f32_e32 v244, v244, v239
	v_fma_f32 v240, v130, v240, v146
	v_fma_f32 v244, v131, v244, v147
	v_lshlrev_b32_e32 v241, 16, v186
	v_and_b32_e32 v245, 0xffff0000, v186
	v_lshlrev_b32_e32 v243, 16, v194
	v_and_b32_e32 v246, 0xffff0000, v194
	v_cndmask_b32_e32 v243, v243, v202, vcc
	v_cndmask_b32_e32 v246, v246, v203, vcc
	v_sub_f32_e32 v243, v243, v241
	v_sub_f32_e32 v246, v246, v245
	v_fmac_f32_e32 v241, v162, v243
	v_fmac_f32_e32 v245, v163, v246
	v_fmac_f32_e32 v240, v234, v241
	v_fmac_f32_e32 v244, v234, v245
	v_mul_f32_e32 v80, v80, v240
	v_mul_f32_e32 v81, v81, v244
	v_lshlrev_b32_e32 v240, 16, v179
	v_and_b32_e32 v244, 0xffff0000, v179
	v_sub_f32_e32 v240, v240, v238
	v_sub_f32_e32 v244, v244, v238
	v_mul_f32_e32 v240, v240, v239
	v_mul_f32_e32 v244, v244, v239
	v_fma_f32 v240, v132, v240, v148
	v_fma_f32 v244, v133, v244, v149
	v_lshlrev_b32_e32 v241, 16, v187
	v_and_b32_e32 v245, 0xffff0000, v187
	v_lshlrev_b32_e32 v243, 16, v195
	v_and_b32_e32 v246, 0xffff0000, v195
	v_cndmask_b32_e32 v243, v243, v204, vcc
	v_cndmask_b32_e32 v246, v246, v205, vcc
	v_sub_f32_e32 v243, v243, v241
	v_sub_f32_e32 v246, v246, v245
	v_fmac_f32_e32 v241, v164, v243
	v_fmac_f32_e32 v245, v165, v246
	v_fmac_f32_e32 v240, v234, v241
	v_fmac_f32_e32 v244, v234, v245
	v_mul_f32_e32 v82, v82, v240
	v_mul_f32_e32 v83, v83, v244
	v_lshlrev_b32_e32 v240, 16, v180
	v_and_b32_e32 v244, 0xffff0000, v180
	v_sub_f32_e32 v240, v240, v238
	v_sub_f32_e32 v244, v244, v238
	v_mul_f32_e32 v240, v240, v239
	v_mul_f32_e32 v244, v244, v239
	v_fma_f32 v240, v134, v240, v150
	v_fma_f32 v244, v135, v244, v151
	v_lshlrev_b32_e32 v241, 16, v188
	v_and_b32_e32 v245, 0xffff0000, v188
	v_lshlrev_b32_e32 v243, 16, v196
	v_and_b32_e32 v246, 0xffff0000, v196
	v_cndmask_b32_e32 v243, v243, v206, vcc
	v_cndmask_b32_e32 v246, v246, v207, vcc
	v_sub_f32_e32 v243, v243, v241
	v_sub_f32_e32 v246, v246, v245
	v_fmac_f32_e32 v241, v166, v243
	v_fmac_f32_e32 v245, v167, v246
	v_fmac_f32_e32 v240, v234, v241
	v_fmac_f32_e32 v244, v234, v245
	v_mul_f32_e32 v84, v84, v240
	v_mul_f32_e32 v85, v85, v244
	v_lshlrev_b32_e32 v240, 16, v181
	v_and_b32_e32 v244, 0xffff0000, v181
	v_sub_f32_e32 v240, v240, v238
; __device__ __forceinline__ float bf2f(u16 h) { return __uint_as_float(((unsigned)h) << 16); }
; template <int EPI> ...
;     ...
;         float d0 = o0 - mean, d1 = o1 - mean;
;         float var = hsum32(d0 * d0 + d1 * d1) * (1.0f / 64.0f);
;         float rstd = rsqrtf(var + 64e-5f);
;         float pv0 = bf2f(P[(size_t)row * 2816 + 256 + 1536 + ch0]);
;         float pv1 = bf2f(P[(size_t)row * 2816 + 256 + 1536 + ch1]);
;         float pp0 = prevP(p, P, row, 1536 + ch0), pp1 = prevP(p, P, row, 1536 + ch1);
;         float vv0 = pv0 + (pp0 - pv0) * mu0, vv1 = pv1 + (pp1 - pv1) * mu1;
;         float b = bs[((size_t)row * 12 + hh) * 4 + 2];
;         float y0 = (d0 * rstd * gg0 + gb0 + b * vv0) * acc0[i];
;         float y1 = (d1 * rstd * gg1 + gb1 + b * vv1) * acc1[i];
;         Y[(size_t)row * 1024 + 256 + ch0] = f2bf(y0);
;         Y[(size_t)row * 1024 + 256 + ch1] = f2bf(y1);
;       }
	v_sub_f32_e32 v244, v244, v238
	v_mul_f32_e32 v240, v240, v239
	v_mul_f32_e32 v244, v244, v239
	v_fma_f32 v240, v136, v240, v152
	v_fma_f32 v244, v137, v244, v153
	v_lshlrev_b32_e32 v241, 16, v189
	v_and_b32_e32 v245, 0xffff0000, v189
	v_lshlrev_b32_e32 v243, 16, v197
	v_and_b32_e32 v246, 0xffff0000, v197
	v_cndmask_b32_e32 v243, v243, v208, vcc
	v_cndmask_b32_e32 v246, v246, v209, vcc
	v_sub_f32_e32 v243, v243, v241
	v_sub_f32_e32 v246, v246, v245
	v_fmac_f32_e32 v241, v168, v243
	v_fmac_f32_e32 v245, v169, v246
	v_fmac_f32_e32 v240, v234, v241
	v_fmac_f32_e32 v244, v234, v245
	v_mul_f32_e32 v86, v86, v240
	v_mul_f32_e32 v87, v87, v244
	v_cvt_pk_bf16_f32 v80, v80, v81
	v_cvt_pk_bf16_f32 v81, v82, v83
	v_cvt_pk_bf16_f32 v82, v84, v85
	v_cvt_pk_bf16_f32 v83, v86, v87
	v_add_u32_e32 v236, 0x10000, v230
	s_nop 0
	global_store_dwordx4 v236, v[80:83], s[22:23] offset:128
	v_lshlrev_b32_e32 v240, 16, v182
	v_and_b32_e32 v244, 0xffff0000, v182
	v_sub_f32_e32 v240, v240, v238
	v_sub_f32_e32 v244, v244, v238
	v_mul_f32_e32 v240, v240, v239
	v_mul_f32_e32 v244, v244, v239
	v_fma_f32 v240, v138, v240, v154
	v_fma_f32 v244, v139, v244, v155
	v_lshlrev_b32_e32 v241, 16, v190
	v_and_b32_e32 v245, 0xffff0000, v190
	v_lshlrev_b32_e32 v243, 16, v198
	v_and_b32_e32 v246, 0xffff0000, v198
	v_cndmask_b32_e32 v243, v243, v210, vcc
	v_cndmask_b32_e32 v246, v246, v211, vcc
	v_sub_f32_e32 v243, v243, v241
	v_sub_f32_e32 v246, v246, v245
	v_fmac_f32_e32 v241, v170, v243
	v_fmac_f32_e32 v245, v171, v246
	v_fmac_f32_e32 v240, v234, v241
	v_fmac_f32_e32 v244, v234, v245
	v_mul_f32_e32 v88, v88, v240
	v_mul_f32_e32 v89, v89, v244
	v_lshlrev_b32_e32 v240, 16, v183
	v_and_b32_e32 v244, 0xffff0000, v183
	v_sub_f32_e32 v240, v240, v238
	v_sub_f32_e32 v244, v244, v238
	v_mul_f32_e32 v240, v240, v239
	v_mul_f32_e32 v244, v244, v239
	v_fma_f32 v240, v140, v240, v156
	v_fma_f32 v244, v141, v244, v157
	v_lshlrev_b32_e32 v241, 16, v191
	v_and_b32_e32 v245, 0xffff0000, v191
	v_lshlrev_b32_e32 v243, 16, v199
	v_and_b32_e32 v246, 0xffff0000, v199
	v_cndmask_b32_e32 v243, v243, v212, vcc
	v_cndmask_b32_e32 v246, v246, v213, vcc
	v_sub_f32_e32 v243, v243, v241
	v_sub_f32_e32 v246, v246, v245
	v_fmac_f32_e32 v241, v172, v243
	v_fmac_f32_e32 v245, v173, v246
	v_fmac_f32_e32 v240, v234, v241
	v_fmac_f32_e32 v244, v234, v245
	v_mul_f32_e32 v90, v90, v240
	v_mul_f32_e32 v91, v91, v244
	v_lshlrev_b32_e32 v240, 16, v184
	v_and_b32_e32 v244, 0xffff0000, v184
	v_sub_f32_e32 v240, v240, v238
	v_sub_f32_e32 v244, v244, v238
	v_mul_f32_e32 v240, v240, v239
	v_mul_f32_e32 v244, v244, v239
	v_fma_f32 v240, v142, v240, v158
	v_fma_f32 v244, v143, v244, v159
	v_lshlrev_b32_e32 v241, 16, v192
	v_and_b32_e32 v245, 0xffff0000, v192
	v_lshlrev_b32_e32 v243, 16, v200
	v_and_b32_e32 v246, 0xffff0000, v200
	v_cndmask_b32_e32 v243, v243, v214, vcc
	v_cndmask_b32_e32 v246, v246, v215, vcc
	v_sub_f32_e32 v243, v243, v241
	v_sub_f32_e32 v246, v246, v245
	v_fmac_f32_e32 v241, v174, v243
	v_fmac_f32_e32 v245, v175, v246
	v_fmac_f32_e32 v240, v234, v241
	v_fmac_f32_e32 v244, v234, v245
	v_mul_f32_e32 v92, v92, v240
	v_mul_f32_e32 v93, v93, v244
	v_lshlrev_b32_e32 v240, 16, v185
	v_and_b32_e32 v244, 0xffff0000, v185
	v_sub_f32_e32 v240, v240, v238
	v_sub_f32_e32 v244, v244, v238
	v_mul_f32_e32 v240, v240, v239
	v_mul_f32_e32 v244, v244, v239
	v_fma_f32 v240, v144, v240, v160
	v_fma_f32 v244, v145, v244, v161
	v_lshlrev_b32_e32 v241, 16, v193
	v_and_b32_e32 v245, 0xffff0000, v193
	v_lshlrev_b32_e32 v243, 16, v201
	v_and_b32_e32 v246, 0xffff0000, v201
	v_cndmask_b32_e32 v243, v243, v216, vcc
	v_cndmask_b32_e32 v246, v246, v217, vcc
	v_sub_f32_e32 v243, v243, v241
	v_sub_f32_e32 v246, v246, v245
	v_fmac_f32_e32 v241, v176, v243
	v_fmac_f32_e32 v245, v177, v246
	v_fmac_f32_e32 v240, v234, v241
	v_fmac_f32_e32 v244, v234, v245
	v_mul_f32_e32 v94, v94, v240
	v_mul_f32_e32 v95, v95, v244
	v_cvt_pk_bf16_f32 v88, v88, v89
	v_cvt_pk_bf16_f32 v89, v90, v91
	v_cvt_pk_bf16_f32 v90, v92, v93
	v_cvt_pk_bf16_f32 v91, v94, v95
	v_add_u32_e32 v236, 0x10000, v230
	s_nop 0
	global_store_dwordx4 v236, v[88:91], s[22:23] offset:192
	v_add_u32_e32 v236, 0x18000, v230
	v_add_u32_e32 v237, 0x42000, v231
	v_subrev_u32_e32 v240, 0x1600, v237
	global_load_dwordx4 v[178:181], v236, s[22:23] offset:128
	global_load_dwordx4 v[182:185], v236, s[22:23] offset:192
	global_load_dwordx4 v[186:189], v237, s[96:97] offset:128
	global_load_dwordx4 v[190:193], v237, s[96:97] offset:192
	global_load_dwordx4 v[194:197], v240, s[96:97] offset:128
	global_load_dwordx4 v[198:201], v240, s[96:97] offset:192
	v_add_u32_e32 v236, 0x2400, v232
	s_nop 0
	global_load_dword v234, v236, s[96:97] offset:16
	v_add_u32_e32 v237, 0x1e000, v247
	global_load_dwordx4 v[202:205], v237, s[20:21] offset:256
	global_load_dwordx4 v[206:209], v237, s[20:21] offset:272
	global_load_dwordx4 v[210:213], v237, s[20:21] offset:384
	global_load_dwordx4 v[214:217], v237, s[20:21] offset:400
	s_waitcnt vmcnt(0)
; __device__ __forceinline__ float bf2f(u16 h) { return __uint_as_float(((unsigned)h) << 16); }
; template <int EPI> ...
;     ...
;       for (int i = 0; i < 16; i++) {
;         const int rl = rbase + (i & 3) + 8 * (i >> 2);
;         const int row = m0 + rl;
;         float o0 = bf2f(Y[(size_t)row * 1024 + 256 + ch0]);
;         float o1 = bf2f(Y[(size_t)row * 1024 + 256 + ch1]);
;         float mean = hsum32(o0 + o1) * (1.0f / 64.0f);
;         float d0 = o0 - mean, d1 = o1 - mean;
;         float var = hsum32(d0 * d0 + d1 * d1) * (1.0f / 64.0f);
;         float rstd = rsqrtf(var + 64e-5f);
;         float pv0 = bf2f(P[(size_t)row * 2816 + 256 + 1536 + ch0]);
;         float pv1 = bf2f(P[(size_t)row * 2816 + 256 + 1536 + ch1]);
;         float pp0 = prevP(p, P, row, 1536 + ch0), pp1 = prevP(p, P, row, 1536 + ch1);
;         float vv0 = pv0 + (pp0 - pv0) * mu0, vv1 = pv1 + (pp1 - pv1) * mu1;
;         float b = bs[((size_t)row * 12 + hh) * 4 + 2];
;         float y0 = (d0 * rstd * gg0 + gb0 + b * vv0) * acc0[i];
;         float y1 = (d1 * rstd * gg1 + gb1 + b * vv1) * acc1[i];
	v_lshlrev_b32_e32 v240, 16, v178
	v_and_b32_e32 v241, 0xffff0000, v178
	v_add_f32_e32 v244, v240, v241
	v_lshlrev_b32_e32 v240, 16, v179
	v_and_b32_e32 v241, 0xffff0000, v179
	v_add_f32_e32 v244, v244, v240
	v_add_f32_e32 v244, v244, v241
	v_lshlrev_b32_e32 v240, 16, v180
	v_and_b32_e32 v241, 0xffff0000, v180
	v_add_f32_e32 v244, v244, v240
	v_add_f32_e32 v244, v244, v241
	v_lshlrev_b32_e32 v240, 16, v181
	v_and_b32_e32 v241, 0xffff0000, v181
	v_add_f32_e32 v244, v244, v240
	v_add_f32_e32 v244, v244, v241
	v_lshlrev_b32_e32 v240, 16, v182
	v_and_b32_e32 v241, 0xffff0000, v182
	v_add_f32_e32 v244, v244, v240
	v_add_f32_e32 v244, v244, v241
	v_lshlrev_b32_e32 v240, 16, v183
	v_and_b32_e32 v241, 0xffff0000, v183
	v_add_f32_e32 v244, v244, v240
	v_add_f32_e32 v244, v244, v241
	v_lshlrev_b32_e32 v240, 16, v184
	v_and_b32_e32 v241, 0xffff0000, v184
	v_add_f32_e32 v244, v244, v240
	v_add_f32_e32 v244, v244, v241
	v_lshlrev_b32_e32 v240, 16, v185
	v_and_b32_e32 v241, 0xffff0000, v185
	v_add_f32_e32 v244, v244, v240
	v_add_f32_e32 v244, v244, v241
	v_mov_b32_e32 v240, v244
	s_nop 1
	v_permlane16_swap_b32_e32 v240, v244
	v_add_f32_e32 v244, v244, v240
	v_mov_b32_e32 v240, v244
	s_nop 1
	v_permlane32_swap_b32_e32 v240, v244
	v_add_f32_e32 v244, v244, v240
	v_mul_f32_e32 v238, 0x3c800000, v244
	v_lshlrev_b32_e32 v240, 16, v178
	v_and_b32_e32 v241, 0xffff0000, v178
	v_sub_f32_e32 v240, v240, v238
	v_sub_f32_e32 v241, v241, v238
	v_mul_f32_e32 v245, v240, v240
	v_fmac_f32_e32 v245, v241, v241
	v_lshlrev_b32_e32 v240, 16, v179
	v_and_b32_e32 v241, 0xffff0000, v179
	v_sub_f32_e32 v240, v240, v238
	v_sub_f32_e32 v241, v241, v238
	v_fmac_f32_e32 v245, v240, v240
	v_fmac_f32_e32 v245, v241, v241
	v_lshlrev_b32_e32 v240, 16, v180
	v_and_b32_e32 v241, 0xffff0000, v180
	v_sub_f32_e32 v240, v240, v238
	v_sub_f32_e32 v241, v241, v238
	v_fmac_f32_e32 v245, v240, v240
	v_fmac_f32_e32 v245, v241, v241
	v_lshlrev_b32_e32 v240, 16, v181
	v_and_b32_e32 v241, 0xffff0000, v181
	v_sub_f32_e32 v240, v240, v238
	v_sub_f32_e32 v241, v241, v238
	v_fmac_f32_e32 v245, v240, v240
	v_fmac_f32_e32 v245, v241, v241
	v_lshlrev_b32_e32 v240, 16, v182
	v_and_b32_e32 v241, 0xffff0000, v182
	v_sub_f32_e32 v240, v240, v238
	v_sub_f32_e32 v241, v241, v238
	v_fmac_f32_e32 v245, v240, v240
	v_fmac_f32_e32 v245, v241, v241
	v_lshlrev_b32_e32 v240, 16, v183
	v_and_b32_e32 v241, 0xffff0000, v183
	v_sub_f32_e32 v240, v240, v238
	v_sub_f32_e32 v241, v241, v238
	v_fmac_f32_e32 v245, v240, v240
	v_fmac_f32_e32 v245, v241, v241
	v_lshlrev_b32_e32 v240, 16, v184
	v_and_b32_e32 v241, 0xffff0000, v184
	v_sub_f32_e32 v240, v240, v238
	v_sub_f32_e32 v241, v241, v238
	v_fmac_f32_e32 v245, v240, v240
	v_fmac_f32_e32 v245, v241, v241
	v_lshlrev_b32_e32 v240, 16, v185
	v_and_b32_e32 v241, 0xffff0000, v185
	v_sub_f32_e32 v240, v240, v238
	v_sub_f32_e32 v241, v241, v238
	v_fmac_f32_e32 v245, v240, v240
	v_fmac_f32_e32 v245, v241, v241
	v_mov_b32_e32 v240, v245
	s_nop 1
	v_permlane16_swap_b32_e32 v240, v245
	v_add_f32_e32 v245, v245, v240
	v_mov_b32_e32 v240, v245
	s_nop 1
	v_permlane32_swap_b32_e32 v240, v245
	v_add_f32_e32 v245, v245, v240
	v_mov_b32_e32 v240, 0x3a27c5ac
	v_fmamk_f32 v245, v245, 0x3c800000, v240
	v_rsq_f32_e32 v239, v245
	v_and_b32_e32 v240, 3, v248
	v_cmp_eq_u32_e32 vcc, 0, v240
	s_nop 1
	v_lshlrev_b32_e32 v240, 16, v178
	v_and_b32_e32 v244, 0xffff0000, v178
	v_sub_f32_e32 v240, v240, v238
	v_sub_f32_e32 v244, v244, v238
	v_mul_f32_e32 v240, v240, v239
	v_mul_f32_e32 v244, v244, v239
	v_fma_f32 v240, v130, v240, v146
	v_fma_f32 v244, v131, v244, v147
	v_lshlrev_b32_e32 v241, 16, v186
	v_and_b32_e32 v245, 0xffff0000, v186
	v_lshlrev_b32_e32 v243, 16, v194
	v_and_b32_e32 v246, 0xffff0000, v194
	v_cndmask_b32_e32 v243, v243, v202, vcc
	v_cndmask_b32_e32 v246, v246, v203, vcc
	v_sub_f32_e32 v243, v243, v241
	v_sub_f32_e32 v246, v246, v245
	v_fmac_f32_e32 v241, v162, v243
	v_fmac_f32_e32 v245, v163, v246
	v_fmac_f32_e32 v240, v234, v241
	v_fmac_f32_e32 v244, v234, v245
	v_mul_f32_e32 v112, v112, v240
	v_mul_f32_e32 v113, v113, v244
	v_lshlrev_b32_e32 v240, 16, v179
	v_and_b32_e32 v244, 0xffff0000, v179
	v_sub_f32_e32 v240, v240, v238
	v_sub_f32_e32 v244, v244, v238
	v_mul_f32_e32 v240, v240, v239
	v_mul_f32_e32 v244, v244, v239
	v_fma_f32 v240, v132, v240, v148
	v_fma_f32 v244, v133, v244, v149
	v_lshlrev_b32_e32 v241, 16, v187
	v_and_b32_e32 v245, 0xffff0000, v187
	v_lshlrev_b32_e32 v243, 16, v195
	v_and_b32_e32 v246, 0xffff0000, v195
	v_cndmask_b32_e32 v243, v243, v204, vcc
	v_cndmask_b32_e32 v246, v246, v205, vcc
	v_sub_f32_e32 v243, v243, v241
	v_sub_f32_e32 v246, v246, v245
	v_fmac_f32_e32 v241, v164, v243
	v_fmac_f32_e32 v245, v165, v246
	v_fmac_f32_e32 v240, v234, v241
	v_fmac_f32_e32 v244, v234, v245
	v_mul_f32_e32 v114, v114, v240
	v_mul_f32_e32 v115, v115, v244
	v_lshlrev_b32_e32 v240, 16, v180
	v_and_b32_e32 v244, 0xffff0000, v180
	v_sub_f32_e32 v240, v240, v238
; __device__ __forceinline__ float bf2f(u16 h) { return __uint_as_float(((unsigned)h) << 16); }
; template <int EPI> ...
;     ...
;         float d0 = o0 - mean, d1 = o1 - mean;
;         float var = hsum32(d0 * d0 + d1 * d1) * (1.0f / 64.0f);
;         float rstd = rsqrtf(var + 64e-5f);
;         float pv0 = bf2f(P[(size_t)row * 2816 + 256 + 1536 + ch0]);
;         float pv1 = bf2f(P[(size_t)row * 2816 + 256 + 1536 + ch1]);
;         float pp0 = prevP(p, P, row, 1536 + ch0), pp1 = prevP(p, P, row, 1536 + ch1);
;         float vv0 = pv0 + (pp0 - pv0) * mu0, vv1 = pv1 + (pp1 - pv1) * mu1;
;         float b = bs[((size_t)row * 12 + hh) * 4 + 2];
;         float y0 = (d0 * rstd * gg0 + gb0 + b * vv0) * acc0[i];
;         float y1 = (d1 * rstd * gg1 + gb1 + b * vv1) * acc1[i];
;         Y[(size_t)row * 1024 + 256 + ch0] = f2bf(y0);
;         Y[(size_t)row * 1024 + 256 + ch1] = f2bf(y1);
;       }
	v_sub_f32_e32 v244, v244, v238
	v_mul_f32_e32 v240, v240, v239
	v_mul_f32_e32 v244, v244, v239
	v_fma_f32 v240, v134, v240, v150
	v_fma_f32 v244, v135, v244, v151
	v_lshlrev_b32_e32 v241, 16, v188
	v_and_b32_e32 v245, 0xffff0000, v188
	v_lshlrev_b32_e32 v243, 16, v196
	v_and_b32_e32 v246, 0xffff0000, v196
	v_cndmask_b32_e32 v243, v243, v206, vcc
	v_cndmask_b32_e32 v246, v246, v207, vcc
	v_sub_f32_e32 v243, v243, v241
	v_sub_f32_e32 v246, v246, v245
	v_fmac_f32_e32 v241, v166, v243
	v_fmac_f32_e32 v245, v167, v246
	v_fmac_f32_e32 v240, v234, v241
	v_fmac_f32_e32 v244, v234, v245
	v_mul_f32_e32 v116, v116, v240
	v_mul_f32_e32 v117, v117, v244
	v_lshlrev_b32_e32 v240, 16, v181
	v_and_b32_e32 v244, 0xffff0000, v181
	v_sub_f32_e32 v240, v240, v238
	v_sub_f32_e32 v244, v244, v238
	v_mul_f32_e32 v240, v240, v239
	v_mul_f32_e32 v244, v244, v239
	v_fma_f32 v240, v136, v240, v152
	v_fma_f32 v244, v137, v244, v153
	v_lshlrev_b32_e32 v241, 16, v189
	v_and_b32_e32 v245, 0xffff0000, v189
	v_lshlrev_b32_e32 v243, 16, v197
	v_and_b32_e32 v246, 0xffff0000, v197
	v_cndmask_b32_e32 v243, v243, v208, vcc
	v_cndmask_b32_e32 v246, v246, v209, vcc
	v_sub_f32_e32 v243, v243, v241
	v_sub_f32_e32 v246, v246, v245
	v_fmac_f32_e32 v241, v168, v243
	v_fmac_f32_e32 v245, v169, v246
	v_fmac_f32_e32 v240, v234, v241
	v_fmac_f32_e32 v244, v234, v245
	v_mul_f32_e32 v118, v118, v240
	v_mul_f32_e32 v119, v119, v244
	v_cvt_pk_bf16_f32 v112, v112, v113
	v_cvt_pk_bf16_f32 v113, v114, v115
	v_cvt_pk_bf16_f32 v114, v116, v117
	v_cvt_pk_bf16_f32 v115, v118, v119
	v_add_u32_e32 v236, 0x18000, v230
	s_nop 0
	global_store_dwordx4 v236, v[112:115], s[22:23] offset:128
	v_lshlrev_b32_e32 v240, 16, v182
	v_and_b32_e32 v244, 0xffff0000, v182
	v_sub_f32_e32 v240, v240, v238
	v_sub_f32_e32 v244, v244, v238
	v_mul_f32_e32 v240, v240, v239
	v_mul_f32_e32 v244, v244, v239
	v_fma_f32 v240, v138, v240, v154
	v_fma_f32 v244, v139, v244, v155
	v_lshlrev_b32_e32 v241, 16, v190
	v_and_b32_e32 v245, 0xffff0000, v190
	v_lshlrev_b32_e32 v243, 16, v198
	v_and_b32_e32 v246, 0xffff0000, v198
	v_cndmask_b32_e32 v243, v243, v210, vcc
	v_cndmask_b32_e32 v246, v246, v211, vcc
	v_sub_f32_e32 v243, v243, v241
	v_sub_f32_e32 v246, v246, v245
	v_fmac_f32_e32 v241, v170, v243
	v_fmac_f32_e32 v245, v171, v246
	v_fmac_f32_e32 v240, v234, v241
	v_fmac_f32_e32 v244, v234, v245
	v_mul_f32_e32 v120, v120, v240
	v_mul_f32_e32 v121, v121, v244
	v_lshlrev_b32_e32 v240, 16, v183
	v_and_b32_e32 v244, 0xffff0000, v183
	v_sub_f32_e32 v240, v240, v238
	v_sub_f32_e32 v244, v244, v238
	v_mul_f32_e32 v240, v240, v239
	v_mul_f32_e32 v244, v244, v239
	v_fma_f32 v240, v140, v240, v156
	v_fma_f32 v244, v141, v244, v157
	v_lshlrev_b32_e32 v241, 16, v191
	v_and_b32_e32 v245, 0xffff0000, v191
	v_lshlrev_b32_e32 v243, 16, v199
	v_and_b32_e32 v246, 0xffff0000, v199
	v_cndmask_b32_e32 v243, v243, v212, vcc
	v_cndmask_b32_e32 v246, v246, v213, vcc
	v_sub_f32_e32 v243, v243, v241
	v_sub_f32_e32 v246, v246, v245
	v_fmac_f32_e32 v241, v172, v243
	v_fmac_f32_e32 v245, v173, v246
	v_fmac_f32_e32 v240, v234, v241
	v_fmac_f32_e32 v244, v234, v245
	v_mul_f32_e32 v122, v122, v240
	v_mul_f32_e32 v123, v123, v244
	v_lshlrev_b32_e32 v240, 16, v184
	v_and_b32_e32 v244, 0xffff0000, v184
	v_sub_f32_e32 v240, v240, v238
	v_sub_f32_e32 v244, v244, v238
	v_mul_f32_e32 v240, v240, v239
	v_mul_f32_e32 v244, v244, v239
	v_fma_f32 v240, v142, v240, v158
	v_fma_f32 v244, v143, v244, v159
	v_lshlrev_b32_e32 v241, 16, v192
	v_and_b32_e32 v245, 0xffff0000, v192
	v_lshlrev_b32_e32 v243, 16, v200
	v_and_b32_e32 v246, 0xffff0000, v200
	v_cndmask_b32_e32 v243, v243, v214, vcc
	v_cndmask_b32_e32 v246, v246, v215, vcc
	v_sub_f32_e32 v243, v243, v241
	v_sub_f32_e32 v246, v246, v245
	v_fmac_f32_e32 v241, v174, v243
	v_fmac_f32_e32 v245, v175, v246
	v_fmac_f32_e32 v240, v234, v241
	v_fmac_f32_e32 v244, v234, v245
	v_mul_f32_e32 v124, v124, v240
	v_mul_f32_e32 v125, v125, v244
	v_lshlrev_b32_e32 v240, 16, v185
	v_and_b32_e32 v244, 0xffff0000, v185
	v_sub_f32_e32 v240, v240, v238
	v_sub_f32_e32 v244, v244, v238
	v_mul_f32_e32 v240, v240, v239
	v_mul_f32_e32 v244, v244, v239
	v_fma_f32 v240, v144, v240, v160
	v_fma_f32 v244, v145, v244, v161
	v_lshlrev_b32_e32 v241, 16, v193
	v_and_b32_e32 v245, 0xffff0000, v193
	v_lshlrev_b32_e32 v243, 16, v201
	v_and_b32_e32 v246, 0xffff0000, v201
	v_cndmask_b32_e32 v243, v243, v216, vcc
	v_cndmask_b32_e32 v246, v246, v217, vcc
	v_sub_f32_e32 v243, v243, v241
	v_sub_f32_e32 v246, v246, v245
	v_fmac_f32_e32 v241, v176, v243
	v_fmac_f32_e32 v245, v177, v246
	v_fmac_f32_e32 v240, v234, v241
	v_fmac_f32_e32 v244, v234, v245
	v_mul_f32_e32 v126, v126, v240
	v_mul_f32_e32 v127, v127, v244
	v_cvt_pk_bf16_f32 v120, v120, v121
	v_cvt_pk_bf16_f32 v121, v122, v123
	v_cvt_pk_bf16_f32 v122, v124, v125
	v_cvt_pk_bf16_f32 v123, v126, v127
	v_add_u32_e32 v236, 0x18000, v230
	s_nop 0
	global_store_dwordx4 v236, v[120:123], s[22:23] offset:192
